# GEMM epilogues: their global loads (row statistics / residual tile / gates) issued before the half-alignment barrier; stacked on saddr + padded-unit skip
# speedup vs baseline: 1.0147x; 1.0147x over previous
.LBB0_47:
	s_add_i32 s23, s23, s25
	v_ashrrev_i32_e32 v215, 31, v214
	v_or_b32_e32 v140, s23, v97
	v_lshlrev_b64 v[182:183], 1, v[214:215]
	v_lshl_add_u64 v[134:135], s[10:11], 0, v[182:183]
	s_ashr_i32 s23, s23, 11
	v_lshlrev_b32_e32 v0, 11, v140
	v_mad_i64_i32 v[136:137], s[42:43], s23, v224, v[134:135]
	v_and_b32_e32 v0, 0x3e7800, v0
	v_lshl_add_u64 v[138:139], v[136:137], 0, v[0:1]
	v_or_b32_e32 v196, 0x8000, v0
	v_mov_b32_e32 v197, v1
	global_load_dwordx4 v[214:217], v[138:139], off
	global_load_dwordx4 v[218:221], v[138:139], off offset:256
	v_lshl_add_u64 v[138:139], v[136:137], 0, v[196:197]
	v_or_b32_e32 v194, 0x10000, v0
	v_mov_b32_e32 v195, v1
	v_or_b32_e32 v192, 0x18000, v0
	v_mov_b32_e32 v193, v1
	global_load_dwordx4 v[236:239], v[138:139], off
	global_load_dwordx4 v[240:243], v[138:139], off offset:256
	v_lshl_add_u64 v[138:139], v[136:137], 0, v[194:195]
	v_lshl_add_u64 v[136:137], v[136:137], 0, v[192:193]
	global_load_dwordx4 v[178:181], v[138:139], off
	global_load_dwordx4 v[174:177], v[138:139], off offset:256
	global_load_dwordx4 v[170:173], v[136:137], off
	global_load_dwordx4 v[166:169], v[136:137], off offset:256
	v_add_u32_e32 v136, 0x80, v140
	v_ashrrev_i32_e32 v244, 11, v136
	s_mov_b32 s44, 0x1414000
	v_lshlrev_b32_e32 v136, 11, v136
	v_mad_i64_i32 v[134:135], s[42:43], v244, s44, v[134:135]
	v_and_b32_e32 v190, 0x3e7800, v136
	v_mov_b32_e32 v191, v1
	v_lshl_add_u64 v[136:137], v[134:135], 0, v[190:191]
	v_or_b32_e32 v188, 0x8000, v190
	v_mov_b32_e32 v189, v1
	global_load_dwordx4 v[162:165], v[136:137], off
	global_load_dwordx4 v[158:161], v[136:137], off offset:256
	v_lshl_add_u64 v[136:137], v[134:135], 0, v[188:189]
	v_or_b32_e32 v186, 0x10000, v190
	v_mov_b32_e32 v187, v1
	v_or_b32_e32 v184, 0x18000, v190
	v_mov_b32_e32 v185, v1
	global_load_dwordx4 v[154:157], v[136:137], off
	global_load_dwordx4 v[150:153], v[136:137], off offset:256
	v_lshl_add_u64 v[136:137], v[134:135], 0, v[186:187]
	v_lshl_add_u64 v[134:135], v[134:135], 0, v[184:185]
	global_load_dwordx4 v[146:149], v[136:137], off
	global_load_dwordx4 v[142:145], v[136:137], off offset:256
	global_load_dwordx4 v[138:141], v[134:135], off
	s_nop 0
	global_load_dwordx4 v[134:137], v[134:135], off offset:256
	s_mul_hi_i32 s31, s23, 0x1414000
	s_mul_i32 s23, s23, 0x1414000
	s_and_b64 vcc, exec, s[20:21]
	s_cbranch_vccz .LBB0_49
	s_barrier
.LBB0_49:
	s_waitcnt vmcnt(0)
	v_lshlrev_b32_e32 v202, 16, v214
	v_and_b32_e32 v203, 0xffff0000, v214
	v_max_f32_e32 v202, v202, v202
	v_max_f32_e32 v203, v203, v203
	v_max_f32_e32 v202, 0xda24260, v202
	v_max_f32_e32 v203, 0xda24260, v203
	v_pk_mul_f32 v[130:131], v[130:131], v[202:203]
	v_lshlrev_b32_e32 v202, 16, v215
	v_and_b32_e32 v203, 0xffff0000, v215
	v_max_f32_e32 v202, v202, v202
	v_max_f32_e32 v203, v203, v203
	v_max_f32_e32 v202, 0xda24260, v202
	v_max_f32_e32 v203, 0xda24260, v203
	v_pk_mul_f32 v[132:133], v[132:133], v[202:203]
	v_lshlrev_b32_e32 v202, 16, v216
	v_and_b32_e32 v203, 0xffff0000, v216
	v_max_f32_e32 v202, v202, v202
	v_max_f32_e32 v203, v203, v203
	v_max_f32_e32 v202, 0xda24260, v202
	v_max_f32_e32 v203, 0xda24260, v203
	v_pk_mul_f32 v[202:203], v[126:127], v[202:203]
	v_lshlrev_b32_e32 v126, 16, v217
	v_and_b32_e32 v127, 0xffff0000, v217
	v_max_f32_e32 v126, v126, v126
	v_max_f32_e32 v127, v127, v127
	s_add_u32 s42, s18, s23
	v_max_f32_e32 v126, 0xda24260, v126
	v_max_f32_e32 v127, 0xda24260, v127
	s_addc_u32 s43, s19, s31
	v_pk_mul_f32 v[214:215], v[128:129], v[126:127]
	v_cvt_pk_bf16_f32 v126, v130, v131
	v_lshl_add_u64 v[130:131], s[42:43], 0, v[0:1]
	v_lshlrev_b32_e32 v0, 16, v218
	v_cvt_pk_bf16_f32 v127, v132, v133
	v_cvt_pk_bf16_f32 v128, v202, v203
	v_cvt_pk_bf16_f32 v129, v214, v215
	v_lshl_add_u64 v[130:131], v[130:131], 0, v[182:183]
	v_max_f32_e32 v0, v0, v0
	global_store_dwordx4 v[130:131], v[126:129], off
	s_andn2_b64 vcc, exec, s[36:37]
	s_mov_b64 s[36:37], -1
	v_max_f32_e32 v126, 0xda24260, v0
	v_and_b32_e32 v0, 0xffff0000, v218
	v_max_f32_e32 v0, v0, v0
	v_max_f32_e32 v127, 0xda24260, v0
	v_lshlrev_b32_e32 v0, 16, v219
	v_max_f32_e32 v0, v0, v0
	v_pk_mul_f32 v[122:123], v[122:123], v[126:127]
	v_max_f32_e32 v126, 0xda24260, v0
	v_and_b32_e32 v0, 0xffff0000, v219
	v_max_f32_e32 v0, v0, v0
	v_max_f32_e32 v127, 0xda24260, v0
	v_lshlrev_b32_e32 v0, 16, v220
	v_max_f32_e32 v0, v0, v0
	v_pk_mul_f32 v[124:125], v[124:125], v[126:127]
	v_max_f32_e32 v126, 0xda24260, v0
	v_and_b32_e32 v0, 0xffff0000, v220
	v_max_f32_e32 v0, v0, v0
	v_max_f32_e32 v127, 0xda24260, v0
	v_lshlrev_b32_e32 v0, 16, v221
	v_max_f32_e32 v0, v0, v0
	v_pk_mul_f32 v[126:127], v[118:119], v[126:127]
	v_max_f32_e32 v118, 0xda24260, v0
	v_and_b32_e32 v0, 0xffff0000, v221
	v_max_f32_e32 v0, v0, v0
	v_max_f32_e32 v119, 0xda24260, v0
	v_pk_mul_f32 v[128:129], v[120:121], v[118:119]
	v_lshlrev_b32_e32 v0, 16, v236
	v_cvt_pk_bf16_f32 v118, v122, v123
	v_cvt_pk_bf16_f32 v119, v124, v125
	v_cvt_pk_bf16_f32 v120, v126, v127
	v_cvt_pk_bf16_f32 v121, v128, v129
	v_max_f32_e32 v0, v0, v0
	global_store_dwordx4 v[130:131], v[118:121], off offset:256
	s_nop 1
	v_max_f32_e32 v118, 0xda24260, v0
	v_and_b32_e32 v0, 0xffff0000, v236
	v_max_f32_e32 v0, v0, v0
	v_max_f32_e32 v119, 0xda24260, v0
	v_lshlrev_b32_e32 v0, 16, v237
	v_max_f32_e32 v0, v0, v0
	v_pk_mul_f32 v[114:115], v[114:115], v[118:119]
	v_max_f32_e32 v118, 0xda24260, v0
	v_and_b32_e32 v0, 0xffff0000, v237
	v_max_f32_e32 v0, v0, v0
	v_max_f32_e32 v119, 0xda24260, v0
	v_lshlrev_b32_e32 v0, 16, v238
	v_max_f32_e32 v0, v0, v0
	v_pk_mul_f32 v[116:117], v[116:117], v[118:119]
	v_max_f32_e32 v118, 0xda24260, v0
	v_and_b32_e32 v0, 0xffff0000, v238
	v_max_f32_e32 v0, v0, v0
	v_max_f32_e32 v119, 0xda24260, v0
	v_lshlrev_b32_e32 v0, 16, v239
	v_max_f32_e32 v0, v0, v0
	v_pk_mul_f32 v[118:119], v[110:111], v[118:119]
	v_max_f32_e32 v110, 0xda24260, v0
	v_and_b32_e32 v0, 0xffff0000, v239
	v_max_f32_e32 v0, v0, v0
	v_max_f32_e32 v111, 0xda24260, v0
	v_pk_mul_f32 v[120:121], v[112:113], v[110:111]
	v_cvt_pk_bf16_f32 v110, v114, v115
	v_lshl_add_u64 v[114:115], s[42:43], 0, v[196:197]
	v_lshlrev_b32_e32 v0, 16, v240
	v_cvt_pk_bf16_f32 v111, v116, v117
	v_cvt_pk_bf16_f32 v112, v118, v119
	v_cvt_pk_bf16_f32 v113, v120, v121
	v_lshl_add_u64 v[114:115], v[114:115], 0, v[182:183]
	v_max_f32_e32 v0, v0, v0
	global_store_dwordx4 v[114:115], v[110:113], off
	s_nop 1
	v_max_f32_e32 v110, 0xda24260, v0
	v_and_b32_e32 v0, 0xffff0000, v240
	v_max_f32_e32 v0, v0, v0
	v_max_f32_e32 v111, 0xda24260, v0
	v_lshlrev_b32_e32 v0, 16, v241
	v_max_f32_e32 v0, v0, v0
	v_pk_mul_f32 v[106:107], v[106:107], v[110:111]
	v_max_f32_e32 v110, 0xda24260, v0
	v_and_b32_e32 v0, 0xffff0000, v241
	v_max_f32_e32 v0, v0, v0
	v_max_f32_e32 v111, 0xda24260, v0
	v_lshlrev_b32_e32 v0, 16, v242
	v_max_f32_e32 v0, v0, v0
	v_pk_mul_f32 v[108:109], v[108:109], v[110:111]
	v_max_f32_e32 v110, 0xda24260, v0
	v_and_b32_e32 v0, 0xffff0000, v242
	v_max_f32_e32 v0, v0, v0
	v_max_f32_e32 v111, 0xda24260, v0
	v_lshlrev_b32_e32 v0, 16, v243
	v_max_f32_e32 v0, v0, v0
	v_pk_mul_f32 v[110:111], v[102:103], v[110:111]
	v_max_f32_e32 v102, 0xda24260, v0
	v_and_b32_e32 v0, 0xffff0000, v243
	v_max_f32_e32 v0, v0, v0
	v_max_f32_e32 v103, 0xda24260, v0
	v_pk_mul_f32 v[112:113], v[104:105], v[102:103]
	v_lshlrev_b32_e32 v0, 16, v178
	v_cvt_pk_bf16_f32 v102, v106, v107
	v_cvt_pk_bf16_f32 v103, v108, v109
	v_cvt_pk_bf16_f32 v104, v110, v111
	v_cvt_pk_bf16_f32 v105, v112, v113
	v_max_f32_e32 v0, v0, v0
	global_store_dwordx4 v[114:115], v[102:105], off offset:256
	s_nop 1
	v_max_f32_e32 v102, 0xda24260, v0
	v_and_b32_e32 v0, 0xffff0000, v178
	v_max_f32_e32 v0, v0, v0
	v_max_f32_e32 v103, 0xda24260, v0
	v_lshlrev_b32_e32 v0, 16, v179
	v_max_f32_e32 v0, v0, v0
	v_pk_mul_f32 v[98:99], v[98:99], v[102:103]
	v_max_f32_e32 v102, 0xda24260, v0
	v_and_b32_e32 v0, 0xffff0000, v179
	v_max_f32_e32 v0, v0, v0
	v_max_f32_e32 v103, 0xda24260, v0
	v_lshlrev_b32_e32 v0, 16, v180
	v_max_f32_e32 v0, v0, v0
	v_pk_mul_f32 v[100:101], v[100:101], v[102:103]
	v_max_f32_e32 v102, 0xda24260, v0
	v_and_b32_e32 v0, 0xffff0000, v180
	v_max_f32_e32 v0, v0, v0
	v_max_f32_e32 v103, 0xda24260, v0
	v_lshlrev_b32_e32 v0, 16, v181
	v_max_f32_e32 v0, v0, v0
	v_pk_mul_f32 v[102:103], v[90:91], v[102:103]
	v_max_f32_e32 v90, 0xda24260, v0
	v_and_b32_e32 v0, 0xffff0000, v181
	v_max_f32_e32 v0, v0, v0
	v_max_f32_e32 v91, 0xda24260, v0
	v_pk_mul_f32 v[104:105], v[92:93], v[90:91]
	v_cvt_pk_bf16_f32 v90, v98, v99
	v_lshl_add_u64 v[98:99], s[42:43], 0, v[194:195]
	v_lshlrev_b32_e32 v0, 16, v174
	v_cvt_pk_bf16_f32 v91, v100, v101
	v_cvt_pk_bf16_f32 v92, v102, v103
	v_cvt_pk_bf16_f32 v93, v104, v105
	v_lshl_add_u64 v[98:99], v[98:99], 0, v[182:183]
	v_max_f32_e32 v0, v0, v0
	global_store_dwordx4 v[98:99], v[90:93], off
	s_nop 1
	v_max_f32_e32 v90, 0xda24260, v0
	v_and_b32_e32 v0, 0xffff0000, v174
	v_max_f32_e32 v0, v0, v0
	v_max_f32_e32 v91, 0xda24260, v0
	v_lshlrev_b32_e32 v0, 16, v175
	v_max_f32_e32 v0, v0, v0
	v_pk_mul_f32 v[86:87], v[86:87], v[90:91]
	v_max_f32_e32 v90, 0xda24260, v0
	v_and_b32_e32 v0, 0xffff0000, v175
	v_max_f32_e32 v0, v0, v0
	v_max_f32_e32 v91, 0xda24260, v0
	v_lshlrev_b32_e32 v0, 16, v176
	v_max_f32_e32 v0, v0, v0
	v_pk_mul_f32 v[88:89], v[88:89], v[90:91]
	v_max_f32_e32 v90, 0xda24260, v0
	v_and_b32_e32 v0, 0xffff0000, v176
	v_max_f32_e32 v0, v0, v0
	v_max_f32_e32 v91, 0xda24260, v0
	v_lshlrev_b32_e32 v0, 16, v177
	v_max_f32_e32 v0, v0, v0
	v_pk_mul_f32 v[90:91], v[82:83], v[90:91]
	v_max_f32_e32 v82, 0xda24260, v0
	v_and_b32_e32 v0, 0xffff0000, v177
	v_max_f32_e32 v0, v0, v0
	v_max_f32_e32 v83, 0xda24260, v0
	v_pk_mul_f32 v[92:93], v[84:85], v[82:83]
	v_lshlrev_b32_e32 v0, 16, v170
	v_cvt_pk_bf16_f32 v82, v86, v87
	v_cvt_pk_bf16_f32 v83, v88, v89
	v_cvt_pk_bf16_f32 v84, v90, v91
	v_cvt_pk_bf16_f32 v85, v92, v93
	v_max_f32_e32 v0, v0, v0
	global_store_dwordx4 v[98:99], v[82:85], off offset:256
	s_nop 1
	v_max_f32_e32 v82, 0xda24260, v0
	v_and_b32_e32 v0, 0xffff0000, v170
	v_max_f32_e32 v0, v0, v0
	v_max_f32_e32 v83, 0xda24260, v0
	v_lshlrev_b32_e32 v0, 16, v171
	v_max_f32_e32 v0, v0, v0
	v_pk_mul_f32 v[78:79], v[78:79], v[82:83]
	v_max_f32_e32 v82, 0xda24260, v0
	v_and_b32_e32 v0, 0xffff0000, v171
	v_max_f32_e32 v0, v0, v0
	v_max_f32_e32 v83, 0xda24260, v0
	v_lshlrev_b32_e32 v0, 16, v172
	v_max_f32_e32 v0, v0, v0
	v_pk_mul_f32 v[80:81], v[80:81], v[82:83]
	v_max_f32_e32 v82, 0xda24260, v0
	v_and_b32_e32 v0, 0xffff0000, v172
	v_max_f32_e32 v0, v0, v0
	v_max_f32_e32 v83, 0xda24260, v0
	v_lshlrev_b32_e32 v0, 16, v173
	v_max_f32_e32 v0, v0, v0
	v_pk_mul_f32 v[82:83], v[74:75], v[82:83]
	v_max_f32_e32 v74, 0xda24260, v0
	v_and_b32_e32 v0, 0xffff0000, v173
	v_max_f32_e32 v0, v0, v0
	v_max_f32_e32 v75, 0xda24260, v0
	v_pk_mul_f32 v[84:85], v[76:77], v[74:75]
	v_cvt_pk_bf16_f32 v74, v78, v79
	v_lshl_add_u64 v[78:79], s[42:43], 0, v[192:193]
	v_lshlrev_b32_e32 v0, 16, v166
	v_cvt_pk_bf16_f32 v75, v80, v81
	v_cvt_pk_bf16_f32 v76, v82, v83
	v_cvt_pk_bf16_f32 v77, v84, v85
	v_lshl_add_u64 v[78:79], v[78:79], 0, v[182:183]
	v_max_f32_e32 v0, v0, v0
	global_store_dwordx4 v[78:79], v[74:77], off
	s_nop 1
	v_max_f32_e32 v74, 0xda24260, v0
	v_and_b32_e32 v0, 0xffff0000, v166
	v_max_f32_e32 v0, v0, v0
	v_max_f32_e32 v75, 0xda24260, v0
	v_lshlrev_b32_e32 v0, 16, v167
	v_max_f32_e32 v0, v0, v0
	v_pk_mul_f32 v[70:71], v[70:71], v[74:75]
	v_max_f32_e32 v74, 0xda24260, v0
	v_and_b32_e32 v0, 0xffff0000, v167
	v_max_f32_e32 v0, v0, v0
	v_max_f32_e32 v75, 0xda24260, v0
	v_lshlrev_b32_e32 v0, 16, v168
	v_max_f32_e32 v0, v0, v0
	v_pk_mul_f32 v[72:73], v[72:73], v[74:75]
	v_max_f32_e32 v74, 0xda24260, v0
	v_and_b32_e32 v0, 0xffff0000, v168
	v_max_f32_e32 v0, v0, v0
	v_max_f32_e32 v75, 0xda24260, v0
	v_lshlrev_b32_e32 v0, 16, v169
	v_max_f32_e32 v0, v0, v0
	v_pk_mul_f32 v[74:75], v[66:67], v[74:75]
	v_max_f32_e32 v66, 0xda24260, v0
	v_and_b32_e32 v0, 0xffff0000, v169
	v_max_f32_e32 v0, v0, v0
	v_max_f32_e32 v67, 0xda24260, v0
	v_pk_mul_f32 v[76:77], v[68:69], v[66:67]
	v_lshlrev_b32_e32 v0, 16, v162
	v_cvt_pk_bf16_f32 v66, v70, v71
	v_cvt_pk_bf16_f32 v67, v72, v73
	v_cvt_pk_bf16_f32 v68, v74, v75
	v_cvt_pk_bf16_f32 v69, v76, v77
	v_max_f32_e32 v0, v0, v0
	global_store_dwordx4 v[78:79], v[66:69], off offset:256
	s_nop 1
	v_max_f32_e32 v66, 0xda24260, v0
	v_and_b32_e32 v0, 0xffff0000, v162
	v_max_f32_e32 v0, v0, v0
	v_max_f32_e32 v67, 0xda24260, v0
	v_lshlrev_b32_e32 v0, 16, v163
	v_max_f32_e32 v0, v0, v0
	v_pk_mul_f32 v[62:63], v[62:63], v[66:67]
	v_max_f32_e32 v66, 0xda24260, v0
	v_and_b32_e32 v0, 0xffff0000, v163
	v_max_f32_e32 v0, v0, v0
	v_max_f32_e32 v67, 0xda24260, v0
	v_lshlrev_b32_e32 v0, 16, v164
	v_max_f32_e32 v0, v0, v0
	v_pk_mul_f32 v[64:65], v[64:65], v[66:67]
	v_max_f32_e32 v66, 0xda24260, v0
	v_and_b32_e32 v0, 0xffff0000, v164
	v_max_f32_e32 v0, v0, v0
	v_max_f32_e32 v67, 0xda24260, v0
	v_lshlrev_b32_e32 v0, 16, v165
	v_max_f32_e32 v0, v0, v0
	v_pk_mul_f32 v[58:59], v[58:59], v[66:67]
	v_max_f32_e32 v66, 0xda24260, v0
	v_and_b32_e32 v0, 0xffff0000, v165
	v_max_f32_e32 v0, v0, v0
	v_max_f32_e32 v67, 0xda24260, v0
	v_pk_mul_f32 v[66:67], v[60:61], v[66:67]
	v_cvt_pk_bf16_f32 v60, v62, v63
	v_cvt_pk_bf16_f32 v62, v58, v59
	v_mov_b64_e32 v[58:59], s[18:19]
	v_mad_i64_i32 v[58:59], s[42:43], v244, s44, v[58:59]
	v_cvt_pk_bf16_f32 v61, v64, v65
	v_lshl_add_u64 v[64:65], v[58:59], 0, v[190:191]
	v_lshlrev_b32_e32 v0, 16, v158
	v_cvt_pk_bf16_f32 v63, v66, v67
	v_lshl_add_u64 v[64:65], v[64:65], 0, v[182:183]
	v_max_f32_e32 v0, v0, v0
	global_store_dwordx4 v[64:65], v[60:63], off
	s_nop 1
	v_max_f32_e32 v60, 0xda24260, v0
	v_and_b32_e32 v0, 0xffff0000, v158
	v_max_f32_e32 v0, v0, v0
	v_max_f32_e32 v61, 0xda24260, v0
	v_lshlrev_b32_e32 v0, 16, v159
	v_max_f32_e32 v0, v0, v0
	v_pk_mul_f32 v[54:55], v[54:55], v[60:61]
	v_max_f32_e32 v60, 0xda24260, v0
	v_and_b32_e32 v0, 0xffff0000, v159
	v_max_f32_e32 v0, v0, v0
	v_max_f32_e32 v61, 0xda24260, v0
	v_lshlrev_b32_e32 v0, 16, v160
	v_max_f32_e32 v0, v0, v0
	v_pk_mul_f32 v[56:57], v[56:57], v[60:61]
	v_max_f32_e32 v60, 0xda24260, v0
	v_and_b32_e32 v0, 0xffff0000, v160
	v_max_f32_e32 v0, v0, v0
	v_max_f32_e32 v61, 0xda24260, v0
	v_lshlrev_b32_e32 v0, 16, v161
	v_max_f32_e32 v0, v0, v0
	v_pk_mul_f32 v[60:61], v[50:51], v[60:61]
	v_max_f32_e32 v50, 0xda24260, v0
	v_and_b32_e32 v0, 0xffff0000, v161
	v_max_f32_e32 v0, v0, v0
	v_max_f32_e32 v51, 0xda24260, v0
	v_pk_mul_f32 v[62:63], v[52:53], v[50:51]
	v_lshlrev_b32_e32 v0, 16, v154
	v_cvt_pk_bf16_f32 v50, v54, v55
	v_cvt_pk_bf16_f32 v51, v56, v57
	v_cvt_pk_bf16_f32 v52, v60, v61
	v_cvt_pk_bf16_f32 v53, v62, v63
	v_max_f32_e32 v0, v0, v0
	global_store_dwordx4 v[64:65], v[50:53], off offset:256
	s_nop 1
	v_max_f32_e32 v50, 0xda24260, v0
	v_and_b32_e32 v0, 0xffff0000, v154
	v_max_f32_e32 v0, v0, v0
	v_max_f32_e32 v51, 0xda24260, v0
	v_lshlrev_b32_e32 v0, 16, v155
	v_max_f32_e32 v0, v0, v0
	v_pk_mul_f32 v[46:47], v[46:47], v[50:51]
	v_max_f32_e32 v50, 0xda24260, v0
	v_and_b32_e32 v0, 0xffff0000, v155
	v_max_f32_e32 v0, v0, v0
	v_max_f32_e32 v51, 0xda24260, v0
	v_lshlrev_b32_e32 v0, 16, v156
	v_max_f32_e32 v0, v0, v0
	v_pk_mul_f32 v[48:49], v[48:49], v[50:51]
	v_max_f32_e32 v50, 0xda24260, v0
	v_and_b32_e32 v0, 0xffff0000, v156
	v_max_f32_e32 v0, v0, v0
	v_max_f32_e32 v51, 0xda24260, v0
	v_lshlrev_b32_e32 v0, 16, v157
	v_max_f32_e32 v0, v0, v0
	v_pk_mul_f32 v[50:51], v[42:43], v[50:51]
	v_max_f32_e32 v42, 0xda24260, v0
	v_and_b32_e32 v0, 0xffff0000, v157
	v_max_f32_e32 v0, v0, v0
	v_max_f32_e32 v43, 0xda24260, v0
	v_pk_mul_f32 v[52:53], v[44:45], v[42:43]
	v_cvt_pk_bf16_f32 v42, v46, v47
	v_lshl_add_u64 v[46:47], v[58:59], 0, v[188:189]
	v_lshlrev_b32_e32 v0, 16, v150
	v_cvt_pk_bf16_f32 v43, v48, v49
	v_cvt_pk_bf16_f32 v44, v50, v51
	v_cvt_pk_bf16_f32 v45, v52, v53
	v_lshl_add_u64 v[46:47], v[46:47], 0, v[182:183]
	v_max_f32_e32 v0, v0, v0
	global_store_dwordx4 v[46:47], v[42:45], off
	s_nop 1
	v_max_f32_e32 v42, 0xda24260, v0
	v_and_b32_e32 v0, 0xffff0000, v150
	v_max_f32_e32 v0, v0, v0
	v_max_f32_e32 v43, 0xda24260, v0
	v_lshlrev_b32_e32 v0, 16, v151
	v_max_f32_e32 v0, v0, v0
	v_pk_mul_f32 v[38:39], v[38:39], v[42:43]
	v_max_f32_e32 v42, 0xda24260, v0
	v_and_b32_e32 v0, 0xffff0000, v151
	v_max_f32_e32 v0, v0, v0
	v_max_f32_e32 v43, 0xda24260, v0
	v_lshlrev_b32_e32 v0, 16, v152
	v_max_f32_e32 v0, v0, v0
	v_pk_mul_f32 v[40:41], v[40:41], v[42:43]
	v_max_f32_e32 v42, 0xda24260, v0
	v_and_b32_e32 v0, 0xffff0000, v152
	v_max_f32_e32 v0, v0, v0
	v_max_f32_e32 v43, 0xda24260, v0
	v_lshlrev_b32_e32 v0, 16, v153
	v_max_f32_e32 v0, v0, v0
	v_pk_mul_f32 v[42:43], v[34:35], v[42:43]
	v_max_f32_e32 v34, 0xda24260, v0
	v_and_b32_e32 v0, 0xffff0000, v153
	v_max_f32_e32 v0, v0, v0
	v_max_f32_e32 v35, 0xda24260, v0
	v_pk_mul_f32 v[44:45], v[36:37], v[34:35]
	v_lshlrev_b32_e32 v0, 16, v146
	v_cvt_pk_bf16_f32 v34, v38, v39
	v_cvt_pk_bf16_f32 v35, v40, v41
	v_cvt_pk_bf16_f32 v36, v42, v43
	v_cvt_pk_bf16_f32 v37, v44, v45
	v_max_f32_e32 v0, v0, v0
	global_store_dwordx4 v[46:47], v[34:37], off offset:256
	s_nop 1
	v_max_f32_e32 v34, 0xda24260, v0
	v_and_b32_e32 v0, 0xffff0000, v146
	v_max_f32_e32 v0, v0, v0
	v_max_f32_e32 v35, 0xda24260, v0
	v_lshlrev_b32_e32 v0, 16, v147
	v_max_f32_e32 v0, v0, v0
	v_pk_mul_f32 v[30:31], v[30:31], v[34:35]
	v_max_f32_e32 v34, 0xda24260, v0
	v_and_b32_e32 v0, 0xffff0000, v147
	v_max_f32_e32 v0, v0, v0
	v_max_f32_e32 v35, 0xda24260, v0
	v_lshlrev_b32_e32 v0, 16, v148
	v_max_f32_e32 v0, v0, v0
	v_pk_mul_f32 v[32:33], v[32:33], v[34:35]
	v_max_f32_e32 v34, 0xda24260, v0
	v_and_b32_e32 v0, 0xffff0000, v148
	v_max_f32_e32 v0, v0, v0
	v_max_f32_e32 v35, 0xda24260, v0
	v_lshlrev_b32_e32 v0, 16, v149
	v_max_f32_e32 v0, v0, v0
	v_pk_mul_f32 v[34:35], v[26:27], v[34:35]
	v_max_f32_e32 v26, 0xda24260, v0
	v_and_b32_e32 v0, 0xffff0000, v149
	v_max_f32_e32 v0, v0, v0
	v_max_f32_e32 v27, 0xda24260, v0
	v_pk_mul_f32 v[36:37], v[28:29], v[26:27]
	v_cvt_pk_bf16_f32 v26, v30, v31
	v_lshl_add_u64 v[30:31], v[58:59], 0, v[186:187]
	v_lshlrev_b32_e32 v0, 16, v142
	v_cvt_pk_bf16_f32 v27, v32, v33
	v_cvt_pk_bf16_f32 v28, v34, v35
	v_cvt_pk_bf16_f32 v29, v36, v37
	v_lshl_add_u64 v[30:31], v[30:31], 0, v[182:183]
	v_max_f32_e32 v0, v0, v0
	global_store_dwordx4 v[30:31], v[26:29], off
	s_nop 1
	v_max_f32_e32 v26, 0xda24260, v0
	v_and_b32_e32 v0, 0xffff0000, v142
	v_max_f32_e32 v0, v0, v0
	v_max_f32_e32 v27, 0xda24260, v0
	v_lshlrev_b32_e32 v0, 16, v143
	v_max_f32_e32 v0, v0, v0
	v_pk_mul_f32 v[22:23], v[22:23], v[26:27]
	v_max_f32_e32 v26, 0xda24260, v0
	v_and_b32_e32 v0, 0xffff0000, v143
	v_max_f32_e32 v0, v0, v0
	v_max_f32_e32 v27, 0xda24260, v0
	v_lshlrev_b32_e32 v0, 16, v144
	v_max_f32_e32 v0, v0, v0
	v_pk_mul_f32 v[24:25], v[24:25], v[26:27]
	v_max_f32_e32 v26, 0xda24260, v0
	v_and_b32_e32 v0, 0xffff0000, v144
	v_max_f32_e32 v0, v0, v0
	v_max_f32_e32 v27, 0xda24260, v0
	v_lshlrev_b32_e32 v0, 16, v145
	v_max_f32_e32 v0, v0, v0
	v_pk_mul_f32 v[26:27], v[18:19], v[26:27]
	v_max_f32_e32 v18, 0xda24260, v0
	v_and_b32_e32 v0, 0xffff0000, v145
	v_max_f32_e32 v0, v0, v0
	v_max_f32_e32 v19, 0xda24260, v0
	v_pk_mul_f32 v[28:29], v[20:21], v[18:19]
	v_lshlrev_b32_e32 v0, 16, v138
	v_cvt_pk_bf16_f32 v18, v22, v23
	v_cvt_pk_bf16_f32 v19, v24, v25
	v_cvt_pk_bf16_f32 v20, v26, v27
	v_cvt_pk_bf16_f32 v21, v28, v29
	v_max_f32_e32 v0, v0, v0
	global_store_dwordx4 v[30:31], v[18:21], off offset:256
	s_nop 1
	v_max_f32_e32 v18, 0xda24260, v0
	v_and_b32_e32 v0, 0xffff0000, v138
	v_max_f32_e32 v0, v0, v0
	v_max_f32_e32 v19, 0xda24260, v0
	v_lshlrev_b32_e32 v0, 16, v139
	v_max_f32_e32 v0, v0, v0
	v_pk_mul_f32 v[14:15], v[14:15], v[18:19]
	v_max_f32_e32 v18, 0xda24260, v0
	v_and_b32_e32 v0, 0xffff0000, v139
	v_max_f32_e32 v0, v0, v0
	v_max_f32_e32 v19, 0xda24260, v0
	v_lshlrev_b32_e32 v0, 16, v140
	v_max_f32_e32 v0, v0, v0
	v_pk_mul_f32 v[16:17], v[16:17], v[18:19]
	v_max_f32_e32 v18, 0xda24260, v0
	v_and_b32_e32 v0, 0xffff0000, v140
	v_max_f32_e32 v0, v0, v0
	v_max_f32_e32 v19, 0xda24260, v0
	v_lshlrev_b32_e32 v0, 16, v141
	v_max_f32_e32 v0, v0, v0
	v_pk_mul_f32 v[18:19], v[10:11], v[18:19]
	v_max_f32_e32 v10, 0xda24260, v0
	v_and_b32_e32 v0, 0xffff0000, v141
	v_max_f32_e32 v0, v0, v0
	v_max_f32_e32 v11, 0xda24260, v0
	v_pk_mul_f32 v[20:21], v[12:13], v[10:11]
	v_cvt_pk_bf16_f32 v10, v14, v15
	v_lshl_add_u64 v[14:15], v[58:59], 0, v[184:185]
	v_lshlrev_b32_e32 v0, 16, v134
	v_cvt_pk_bf16_f32 v11, v16, v17
	v_cvt_pk_bf16_f32 v12, v18, v19
	v_cvt_pk_bf16_f32 v13, v20, v21
	v_lshl_add_u64 v[14:15], v[14:15], 0, v[182:183]
	v_max_f32_e32 v0, v0, v0
	global_store_dwordx4 v[14:15], v[10:13], off
	s_nop 1
	v_max_f32_e32 v10, 0xda24260, v0
	v_and_b32_e32 v0, 0xffff0000, v134
	v_max_f32_e32 v0, v0, v0
	v_max_f32_e32 v11, 0xda24260, v0
	v_lshlrev_b32_e32 v0, 16, v135
	v_max_f32_e32 v0, v0, v0
	v_pk_mul_f32 v[6:7], v[6:7], v[10:11]
	v_max_f32_e32 v10, 0xda24260, v0
	v_and_b32_e32 v0, 0xffff0000, v135
	v_max_f32_e32 v0, v0, v0
	v_max_f32_e32 v11, 0xda24260, v0
	v_lshlrev_b32_e32 v0, 16, v136
	v_max_f32_e32 v0, v0, v0
	v_pk_mul_f32 v[8:9], v[8:9], v[10:11]
	v_max_f32_e32 v10, 0xda24260, v0
	v_and_b32_e32 v0, 0xffff0000, v136
	v_max_f32_e32 v0, v0, v0
	v_max_f32_e32 v11, 0xda24260, v0
	v_lshlrev_b32_e32 v0, 16, v137
	v_max_f32_e32 v0, v0, v0
	v_pk_mul_f32 v[10:11], v[2:3], v[10:11]
	v_max_f32_e32 v2, 0xda24260, v0
	v_and_b32_e32 v0, 0xffff0000, v137
	v_max_f32_e32 v0, v0, v0
	v_max_f32_e32 v3, 0xda24260, v0
	v_pk_mul_f32 v[12:13], v[4:5], v[2:3]
	v_cvt_pk_bf16_f32 v2, v6, v7
	v_cvt_pk_bf16_f32 v3, v8, v9
	v_cvt_pk_bf16_f32 v4, v10, v11
	v_cvt_pk_bf16_f32 v5, v12, v13
	global_store_dwordx4 v[14:15], v[2:5], off offset:256
	s_cbranch_vccnz .LBB0_36
	s_andn2_b64 vcc, exec, s[0:1]
	s_cbranch_vccnz .LBB0_35
	s_barrier
	s_branch .LBB0_35

.Lwinskip_7:
	s_setprio 0
	s_barrier
	s_add_i32 s74, s74, 2
	s_add_u32 s72, s72, 0x100
	s_addc_u32 s73, s73, 0
	s_add_u32 s64, s64, 0x100
	s_addc_u32 s65, s65, 0
	s_cmp_gt_u32 s74, 13
	s_cbranch_scc0 .LBB0_403
	s_lshl_b32 s57, s6, 8
	s_add_i32 s57, s57, s28
	v_or_b32_e32 v184, s57, v97
	v_or_b32_e32 v136, 16, v184
	v_ashrrev_i32_e32 v137, 31, v136
	v_or_b32_e32 v138, 32, v184
	v_lshl_add_u64 v[136:137], v[136:137], 4, s[16:17]
	v_ashrrev_i32_e32 v139, 31, v138
	v_lshl_add_u64 v[138:139], v[138:139], 4, s[16:17]
	global_load_dwordx4 v[154:157], v[136:137], off
	global_load_dwordx4 v[142:145], v[138:139], off
	v_or_b32_e32 v136, 48, v184
	v_add_u32_e32 v182, 0x80, v184
	v_ashrrev_i32_e32 v185, 31, v184
	v_ashrrev_i32_e32 v137, 31, v136
	v_ashrrev_i32_e32 v183, 31, v182
	v_lshl_add_u64 v[134:135], v[184:185], 4, s[16:17]
	v_lshl_add_u64 v[136:137], v[136:137], 4, s[16:17]
	v_lshl_add_u64 v[138:139], v[182:183], 4, s[16:17]
	global_load_dwordx4 v[158:161], v[136:137], off
	global_load_dwordx4 v[150:153], v[138:139], off
	global_load_dwordx4 v[162:165], v[134:135], off
	global_load_dwordx4 v[146:149], v[134:135], off offset:2304
	s_nop 0
	global_load_dwordx4 v[138:141], v[134:135], off offset:2560
	s_nop 0
	global_load_dwordx4 v[134:137], v[134:135], off offset:2816
	s_and_b64 vcc, exec, s[30:31]
	s_cbranch_vccz .LBB0_406
	s_barrier
.LBB0_406:
	s_lshl_b32 s59, s78, 1
	s_cmp_gt_i32 s78, 1
	s_mov_b64 s[66:67], -1
	s_cbranch_scc0 .LBB0_419
	s_cmp_lt_i32 s78, 3
	s_mov_b64 s[66:67], 0
	s_cbranch_scc1 .LBB0_418
	s_cmp_lt_i32 s78, 4
	s_mov_b64 s[76:77], -1
	s_cbranch_scc1 .LBB0_504
	s_cmp_lg_u32 s78, 4
	s_cbranch_scc0 .LBB0_501
	s_cmp_gt_u32 s59, 13
	s_cbranch_scc0 .LBB0_498
	s_cmp_gt_u32 s59, 17
	s_mov_b64 s[74:75], -1
	s_cbranch_scc0 .LBB0_496
	s_cmp_gt_u32 s59, 21
	s_mov_b64 s[72:73], -1
	s_cbranch_scc0 .LBB0_494
	s_cmp_gt_u32 s59, 29
	s_cbranch_scc0 .LBB0_491
	s_cmp_gt_u32 s59, 37
	s_mov_b64 s[64:65], -1
	s_cbranch_scc0 .LBB0_416
	s_cmp_eq_u32 s78, 19
	s_mov_b64 s[64:65], 0
	s_cselect_b64 s[68:69], -1, 0

.LBB0_528:
	s_add_i32 s53, s30, 2
	s_add_u32 s54, s22, 0x80
	s_addc_u32 s31, s23, 0
	s_add_i32 s56, 0, 0x10000
	s_cmp_eq_u32 s46, s30
	s_cselect_b32 s31, s1, s31
	s_cselect_b32 s30, s0, s54
	s_cselect_b32 s55, s21, s52
	s_cselect_b32 s54, s20, s51
	s_add_i32 s57, 0, 0x14000
	v_add_u32_e32 v152, s56, v232
	v_add_u32_e32 v168, s57, v232
	ds_read_b128 v[140:143], v152
	ds_read_b128 v[144:147], v152 offset:1024
	ds_read_b128 v[148:151], v152 offset:2048
	ds_read_b128 v[152:155], v152 offset:3072
	ds_read_b128 v[156:159], v168
	ds_read_b128 v[160:163], v168 offset:1024
	ds_read_b128 v[164:167], v168 offset:2048
	ds_read_b128 v[168:171], v168 offset:3072
	s_add_i32 m0, s28, 0xc000
	ds_read_b128 v[172:175], v236
	ds_read_b128 v[176:179], v236 offset:1024
	ds_read_b128 v[180:183], v236 offset:2048
	ds_read_b128 v[184:187], v236 offset:3072
	ds_read_b128 v[188:191], v236 offset:4096
	ds_read_b128 v[192:195], v236 offset:5120
	ds_read_b128 v[208:211], v236 offset:6144
	ds_read_b128 v[212:215], v236 offset:7168
	global_load_lds_dwordx4 v138, s[22:23]
	s_add_i32 m0, s28, 0xe000
	s_nop 0
	global_load_lds_dwordx4 v136, s[22:23]
	s_waitcnt vmcnt(8)
	s_waitcnt lgkmcnt(0)
	s_barrier
	s_setprio 1
	s_waitcnt lgkmcnt(0)
	v_mfma_f32_16x16x32_bf16 v[130:133], v[140:143], v[172:175], v[130:133]
	v_mfma_f32_16x16x32_bf16 v[126:129], v[148:151], v[172:175], v[126:129]
	v_mfma_f32_16x16x32_bf16 v[114:117], v[140:143], v[180:183], v[114:117]
	v_mfma_f32_16x16x32_bf16 v[110:113], v[148:151], v[180:183], v[110:113]
	v_mfma_f32_16x16x32_bf16 v[98:101], v[140:143], v[188:191], v[98:101]
	v_mfma_f32_16x16x32_bf16 v[90:93], v[148:151], v[188:191], v[90:93]
	v_mfma_f32_16x16x32_bf16 v[78:81], v[140:143], v[208:211], v[78:81]
	v_mfma_f32_16x16x32_bf16 v[74:77], v[148:151], v[208:211], v[74:77]
	v_mfma_f32_16x16x32_bf16 v[130:133], v[144:147], v[176:179], v[130:133]
	v_mfma_f32_16x16x32_bf16 v[126:129], v[152:155], v[176:179], v[126:129]
	v_mfma_f32_16x16x32_bf16 v[114:117], v[144:147], v[184:187], v[114:117]
	v_mfma_f32_16x16x32_bf16 v[110:113], v[152:155], v[184:187], v[110:113]
	v_mfma_f32_16x16x32_bf16 v[98:101], v[144:147], v[192:195], v[98:101]
	v_mfma_f32_16x16x32_bf16 v[90:93], v[152:155], v[192:195], v[90:93]
	v_mfma_f32_16x16x32_bf16 v[78:81], v[144:147], v[212:215], v[78:81]
	v_mfma_f32_16x16x32_bf16 v[74:77], v[152:155], v[212:215], v[74:77]
	s_setprio 0
	s_setprio 1
	v_mfma_f32_16x16x32_bf16 v[122:125], v[156:159], v[172:175], v[122:125]
	v_mfma_f32_16x16x32_bf16 v[118:121], v[164:167], v[172:175], v[118:121]
	v_mfma_f32_16x16x32_bf16 v[106:109], v[156:159], v[180:183], v[106:109]
	v_mfma_f32_16x16x32_bf16 v[102:105], v[164:167], v[180:183], v[102:105]
	v_mfma_f32_16x16x32_bf16 v[86:89], v[156:159], v[188:191], v[86:89]
	v_mfma_f32_16x16x32_bf16 v[82:85], v[164:167], v[188:191], v[82:85]
	v_mfma_f32_16x16x32_bf16 v[70:73], v[156:159], v[208:211], v[70:73]
	v_mfma_f32_16x16x32_bf16 v[66:69], v[164:167], v[208:211], v[66:69]
	v_mfma_f32_16x16x32_bf16 v[122:125], v[160:163], v[176:179], v[122:125]
	v_mfma_f32_16x16x32_bf16 v[118:121], v[168:171], v[176:179], v[118:121]
	v_mfma_f32_16x16x32_bf16 v[106:109], v[160:163], v[184:187], v[106:109]
	v_mfma_f32_16x16x32_bf16 v[102:105], v[168:171], v[184:187], v[102:105]
	v_mfma_f32_16x16x32_bf16 v[86:89], v[160:163], v[192:195], v[86:89]
	v_mfma_f32_16x16x32_bf16 v[82:85], v[168:171], v[192:195], v[82:85]
	v_mfma_f32_16x16x32_bf16 v[70:73], v[160:163], v[212:215], v[70:73]
	v_mfma_f32_16x16x32_bf16 v[66:69], v[168:171], v[212:215], v[66:69]
	s_setprio 0
	s_barrier
	s_add_i32 s56, s56, s25
	s_mov_b32 m0, s56
	ds_read_b128 v[172:175], v236 offset:16384
	ds_read_b128 v[176:179], v236 offset:17408
	ds_read_b128 v[180:183], v236 offset:18432
	ds_read_b128 v[184:187], v236 offset:19456
	ds_read_b128 v[188:191], v236 offset:20480
	ds_read_b128 v[192:195], v236 offset:21504
	ds_read_b128 v[208:211], v236 offset:22528
	ds_read_b128 v[212:215], v236 offset:23552
	global_load_lds_dwordx4 v0, s[54:55]
	s_add_i32 m0, s56, 0x2000
	s_nop 0
	global_load_lds_dwordx4 v94, s[54:55]
	s_add_u32 s54, s54, s6
	s_addc_u32 s55, s55, 0
	s_add_i32 s56, s57, s25
	s_mov_b32 m0, s56
	s_nop 0
	global_load_lds_dwordx4 v0, s[54:55]
	s_add_i32 m0, s56, 0x2000
	s_nop 0
	global_load_lds_dwordx4 v94, s[54:55]
	s_mov_b32 m0, s28
	s_nop 0
	global_load_lds_dwordx4 v0, s[30:31]
	s_mov_b32 m0, s29
	s_nop 0
	global_load_lds_dwordx4 v94, s[30:31]
	s_waitcnt vmcnt(8)
	s_waitcnt lgkmcnt(0)
	s_barrier
	s_setprio 1
	s_waitcnt lgkmcnt(0)
	v_mfma_f32_16x16x32_bf16 v[62:65], v[140:143], v[172:175], v[62:65]
	v_mfma_f32_16x16x32_bf16 v[58:61], v[148:151], v[172:175], v[58:61]
	v_mfma_f32_16x16x32_bf16 v[46:49], v[140:143], v[180:183], v[46:49]
	v_mfma_f32_16x16x32_bf16 v[42:45], v[148:151], v[180:183], v[42:45]
	v_mfma_f32_16x16x32_bf16 v[30:33], v[140:143], v[188:191], v[30:33]
	v_mfma_f32_16x16x32_bf16 v[26:29], v[148:151], v[188:191], v[26:29]
	v_mfma_f32_16x16x32_bf16 v[14:17], v[140:143], v[208:211], v[14:17]
	v_mfma_f32_16x16x32_bf16 v[10:13], v[148:151], v[208:211], v[10:13]
	v_mfma_f32_16x16x32_bf16 v[62:65], v[144:147], v[176:179], v[62:65]
	v_mfma_f32_16x16x32_bf16 v[58:61], v[152:155], v[176:179], v[58:61]
	v_mfma_f32_16x16x32_bf16 v[46:49], v[144:147], v[184:187], v[46:49]
	v_mfma_f32_16x16x32_bf16 v[42:45], v[152:155], v[184:187], v[42:45]
	v_mfma_f32_16x16x32_bf16 v[30:33], v[144:147], v[192:195], v[30:33]
	v_mfma_f32_16x16x32_bf16 v[26:29], v[152:155], v[192:195], v[26:29]
	v_mfma_f32_16x16x32_bf16 v[14:17], v[144:147], v[212:215], v[14:17]
	v_mfma_f32_16x16x32_bf16 v[10:13], v[152:155], v[212:215], v[10:13]
	s_setprio 0
	s_setprio 1
	v_mfma_f32_16x16x32_bf16 v[54:57], v[156:159], v[172:175], v[54:57]
	v_mfma_f32_16x16x32_bf16 v[50:53], v[164:167], v[172:175], v[50:53]
	v_mfma_f32_16x16x32_bf16 v[38:41], v[156:159], v[180:183], v[38:41]
	v_mfma_f32_16x16x32_bf16 v[34:37], v[164:167], v[180:183], v[34:37]
	v_mfma_f32_16x16x32_bf16 v[22:25], v[156:159], v[188:191], v[22:25]
	v_mfma_f32_16x16x32_bf16 v[18:21], v[164:167], v[188:191], v[18:21]
	v_mfma_f32_16x16x32_bf16 v[6:9], v[156:159], v[208:211], v[6:9]
	v_mfma_f32_16x16x32_bf16 v[2:5], v[164:167], v[208:211], v[2:5]
	v_mfma_f32_16x16x32_bf16 v[54:57], v[160:163], v[176:179], v[54:57]
	v_mfma_f32_16x16x32_bf16 v[50:53], v[168:171], v[176:179], v[50:53]
	v_mfma_f32_16x16x32_bf16 v[38:41], v[160:163], v[184:187], v[38:41]
	v_mfma_f32_16x16x32_bf16 v[34:37], v[168:171], v[184:187], v[34:37]
	v_mfma_f32_16x16x32_bf16 v[22:25], v[160:163], v[192:195], v[22:25]
	v_mfma_f32_16x16x32_bf16 v[18:21], v[168:171], v[192:195], v[18:21]
	v_mfma_f32_16x16x32_bf16 v[6:9], v[160:163], v[212:215], v[6:9]
	v_mfma_f32_16x16x32_bf16 v[2:5], v[168:171], v[212:215], v[2:5]
	s_setprio 0
	s_barrier
	s_add_i32 s56, 0, 0x18000
	s_add_i32 s57, 0, 0x1c000
	v_add_u32_e32 v152, s56, v232
	v_add_u32_e32 v168, s57, v232
	ds_read_b128 v[140:143], v152
	ds_read_b128 v[144:147], v152 offset:1024
	ds_read_b128 v[148:151], v152 offset:2048
	ds_read_b128 v[152:155], v152 offset:3072
	ds_read_b128 v[156:159], v168
	ds_read_b128 v[160:163], v168 offset:1024
	ds_read_b128 v[164:167], v168 offset:2048
	ds_read_b128 v[168:171], v168 offset:3072
	s_add_u32 s30, s30, s6
	s_addc_u32 s31, s31, 0
	s_mov_b32 m0, s33
	ds_read_b128 v[172:175], v236 offset:32768
	ds_read_b128 v[176:179], v236 offset:33792
	ds_read_b128 v[180:183], v236 offset:34816
	ds_read_b128 v[184:187], v236 offset:35840
	ds_read_b128 v[188:191], v236 offset:36864
	ds_read_b128 v[192:195], v236 offset:37888
	ds_read_b128 v[208:211], v236 offset:38912
	ds_read_b128 v[212:215], v236 offset:39936
	global_load_lds_dwordx4 v0, s[30:31]
	s_mov_b32 m0, s42
	s_nop 0
	global_load_lds_dwordx4 v94, s[30:31]
	s_waitcnt vmcnt(8)
	s_waitcnt lgkmcnt(0)
	s_barrier
	s_setprio 1
	s_waitcnt lgkmcnt(0)
	v_mfma_f32_16x16x32_bf16 v[130:133], v[140:143], v[172:175], v[130:133]
	v_mfma_f32_16x16x32_bf16 v[126:129], v[148:151], v[172:175], v[126:129]
	v_mfma_f32_16x16x32_bf16 v[114:117], v[140:143], v[180:183], v[114:117]
	v_mfma_f32_16x16x32_bf16 v[110:113], v[148:151], v[180:183], v[110:113]
	v_mfma_f32_16x16x32_bf16 v[98:101], v[140:143], v[188:191], v[98:101]
	v_mfma_f32_16x16x32_bf16 v[90:93], v[148:151], v[188:191], v[90:93]
	v_mfma_f32_16x16x32_bf16 v[78:81], v[140:143], v[208:211], v[78:81]
	v_mfma_f32_16x16x32_bf16 v[74:77], v[148:151], v[208:211], v[74:77]
	v_mfma_f32_16x16x32_bf16 v[130:133], v[144:147], v[176:179], v[130:133]
	v_mfma_f32_16x16x32_bf16 v[126:129], v[152:155], v[176:179], v[126:129]
	v_mfma_f32_16x16x32_bf16 v[114:117], v[144:147], v[184:187], v[114:117]
	v_mfma_f32_16x16x32_bf16 v[110:113], v[152:155], v[184:187], v[110:113]
	v_mfma_f32_16x16x32_bf16 v[98:101], v[144:147], v[192:195], v[98:101]
	v_mfma_f32_16x16x32_bf16 v[90:93], v[152:155], v[192:195], v[90:93]
	v_mfma_f32_16x16x32_bf16 v[78:81], v[144:147], v[212:215], v[78:81]
	v_mfma_f32_16x16x32_bf16 v[74:77], v[152:155], v[212:215], v[74:77]
	s_setprio 0
	s_setprio 1
	v_mfma_f32_16x16x32_bf16 v[122:125], v[156:159], v[172:175], v[122:125]
	v_mfma_f32_16x16x32_bf16 v[118:121], v[164:167], v[172:175], v[118:121]
	v_mfma_f32_16x16x32_bf16 v[106:109], v[156:159], v[180:183], v[106:109]
	v_mfma_f32_16x16x32_bf16 v[102:105], v[164:167], v[180:183], v[102:105]
	v_mfma_f32_16x16x32_bf16 v[86:89], v[156:159], v[188:191], v[86:89]
	v_mfma_f32_16x16x32_bf16 v[82:85], v[164:167], v[188:191], v[82:85]
	v_mfma_f32_16x16x32_bf16 v[70:73], v[156:159], v[208:211], v[70:73]
	v_mfma_f32_16x16x32_bf16 v[66:69], v[164:167], v[208:211], v[66:69]
	v_mfma_f32_16x16x32_bf16 v[122:125], v[160:163], v[176:179], v[122:125]
	v_mfma_f32_16x16x32_bf16 v[118:121], v[168:171], v[176:179], v[118:121]
	v_mfma_f32_16x16x32_bf16 v[106:109], v[160:163], v[184:187], v[106:109]
	v_mfma_f32_16x16x32_bf16 v[102:105], v[168:171], v[184:187], v[102:105]
	v_mfma_f32_16x16x32_bf16 v[86:89], v[160:163], v[192:195], v[86:89]
	v_mfma_f32_16x16x32_bf16 v[82:85], v[168:171], v[192:195], v[82:85]
	v_mfma_f32_16x16x32_bf16 v[70:73], v[160:163], v[212:215], v[70:73]
	v_mfma_f32_16x16x32_bf16 v[66:69], v[168:171], v[212:215], v[66:69]
	s_setprio 0
	s_barrier
	s_add_i32 s71, s56, s25
	s_sub_u32 s54, s54, s6
	s_subb_u32 s55, s55, 0
	s_add_u32 s54, s54, 0x80
	s_addc_u32 s55, s55, 0
	s_mov_b32 m0, s71
	ds_read_b128 v[172:175], v236 offset:49152
	ds_read_b128 v[176:179], v236 offset:50176
	ds_read_b128 v[180:183], v236 offset:51200
	ds_read_b128 v[184:187], v236 offset:52224
	ds_read_b128 v[188:191], v236 offset:53248
	ds_read_b128 v[192:195], v236 offset:54272
	ds_read_b128 v[208:211], v236 offset:55296
	ds_read_b128 v[212:215], v236 offset:56320
	global_load_lds_dwordx4 v0, s[54:55]
	s_add_i32 m0, s71, 0x2000
	s_nop 0
	global_load_lds_dwordx4 v94, s[54:55]
	s_add_i32 s71, s57, s25
	s_add_u32 s54, s54, s6
	s_addc_u32 s55, s55, 0
	s_mov_b32 m0, s71
	s_nop 0
	global_load_lds_dwordx4 v0, s[54:55]
	s_add_i32 m0, s71, 0x2000
	s_nop 0
	global_load_lds_dwordx4 v94, s[54:55]
	s_sub_u32 s30, s30, s6
	s_subb_u32 s31, s31, 0
	s_add_u32 s30, s30, 0x80
	s_addc_u32 s31, s31, 0
	s_mov_b32 m0, s43
	s_nop 0
	global_load_lds_dwordx4 v0, s[30:31]
	s_mov_b32 m0, s44
	s_nop 0
	global_load_lds_dwordx4 v94, s[30:31]
	s_waitcnt vmcnt(8)
	s_waitcnt lgkmcnt(0)
	s_barrier
	s_setprio 1
	s_waitcnt lgkmcnt(0)
	v_mfma_f32_16x16x32_bf16 v[62:65], v[140:143], v[172:175], v[62:65]
	v_mfma_f32_16x16x32_bf16 v[58:61], v[148:151], v[172:175], v[58:61]
	v_mfma_f32_16x16x32_bf16 v[46:49], v[140:143], v[180:183], v[46:49]
	v_mfma_f32_16x16x32_bf16 v[42:45], v[148:151], v[180:183], v[42:45]
	v_mfma_f32_16x16x32_bf16 v[30:33], v[140:143], v[188:191], v[30:33]
	v_mfma_f32_16x16x32_bf16 v[26:29], v[148:151], v[188:191], v[26:29]
	v_mfma_f32_16x16x32_bf16 v[14:17], v[140:143], v[208:211], v[14:17]
	v_mfma_f32_16x16x32_bf16 v[10:13], v[148:151], v[208:211], v[10:13]
	v_mfma_f32_16x16x32_bf16 v[62:65], v[144:147], v[176:179], v[62:65]
	v_mfma_f32_16x16x32_bf16 v[58:61], v[152:155], v[176:179], v[58:61]
	v_mfma_f32_16x16x32_bf16 v[46:49], v[144:147], v[184:187], v[46:49]
	v_mfma_f32_16x16x32_bf16 v[42:45], v[152:155], v[184:187], v[42:45]
	v_mfma_f32_16x16x32_bf16 v[30:33], v[144:147], v[192:195], v[30:33]
	v_mfma_f32_16x16x32_bf16 v[26:29], v[152:155], v[192:195], v[26:29]
	v_mfma_f32_16x16x32_bf16 v[14:17], v[144:147], v[212:215], v[14:17]
	v_mfma_f32_16x16x32_bf16 v[10:13], v[152:155], v[212:215], v[10:13]
	s_setprio 0
	s_setprio 1
	v_mfma_f32_16x16x32_bf16 v[54:57], v[156:159], v[172:175], v[54:57]
	v_mfma_f32_16x16x32_bf16 v[50:53], v[164:167], v[172:175], v[50:53]
	v_mfma_f32_16x16x32_bf16 v[38:41], v[156:159], v[180:183], v[38:41]
	v_mfma_f32_16x16x32_bf16 v[34:37], v[164:167], v[180:183], v[34:37]
	v_mfma_f32_16x16x32_bf16 v[22:25], v[156:159], v[188:191], v[22:25]
	v_mfma_f32_16x16x32_bf16 v[18:21], v[164:167], v[188:191], v[18:21]
	v_mfma_f32_16x16x32_bf16 v[6:9], v[156:159], v[208:211], v[6:9]
	v_mfma_f32_16x16x32_bf16 v[2:5], v[164:167], v[208:211], v[2:5]
	v_mfma_f32_16x16x32_bf16 v[54:57], v[160:163], v[176:179], v[54:57]
	v_mfma_f32_16x16x32_bf16 v[50:53], v[168:171], v[176:179], v[50:53]
	v_mfma_f32_16x16x32_bf16 v[38:41], v[160:163], v[184:187], v[38:41]
	v_mfma_f32_16x16x32_bf16 v[34:37], v[168:171], v[184:187], v[34:37]
	v_mfma_f32_16x16x32_bf16 v[22:25], v[160:163], v[192:195], v[22:25]
	v_mfma_f32_16x16x32_bf16 v[18:21], v[168:171], v[192:195], v[18:21]
	v_mfma_f32_16x16x32_bf16 v[6:9], v[160:163], v[212:215], v[6:9]
	v_mfma_f32_16x16x32_bf16 v[2:5], v[168:171], v[212:215], v[2:5]
	s_setprio 0
	s_barrier
	s_add_u32 s51, s51, 0x100
	s_addc_u32 s52, s52, 0
	s_add_u32 s22, s22, 0x100
	s_addc_u32 s23, s23, 0
	s_cmp_ge_u32 s53, s45
	s_mov_b32 s30, s53
	s_cbranch_scc0 .LBB0_528
	s_lshl_b32 s19, s19, 8
	v_and_b32_e32 v196, 0xe0, v233
	v_and_b32_e32 v197, 4, v233
	v_lshl_add_u32 v196, v197, 2, v196
	v_and_b32_e32 v197, 8, v233
	v_add_u32_e32 v196, v196, v197
	v_lshl_add_u32 v196, s18, 8, v196
	v_lshlrev_b32_e32 v196, 1, v196
	v_lshl_add_u32 v196, v97, 11, v196
	s_lshl_b32 s22, s19, 11
	s_add_u32 s22, s14, s22
	s_addc_u32 s23, s15, 0
	s_nop 1
	global_load_dwordx4 v[140:143], v196, s[22:23]
	global_load_dwordx4 v[144:147], v196, s[22:23] offset:256
	s_add_u32 s22, s22, 0x8000
	s_addc_u32 s23, s23, 0
	s_nop 1
	global_load_dwordx4 v[148:151], v196, s[22:23]
	global_load_dwordx4 v[152:155], v196, s[22:23] offset:256
	s_add_u32 s22, s22, 0x8000
	s_addc_u32 s23, s23, 0
	s_nop 1
	global_load_dwordx4 v[156:159], v196, s[22:23]
	global_load_dwordx4 v[160:163], v196, s[22:23] offset:256
	s_add_u32 s22, s22, 0x8000
	s_addc_u32 s23, s23, 0
	s_nop 1
	global_load_dwordx4 v[164:167], v196, s[22:23]
	global_load_dwordx4 v[168:171], v196, s[22:23] offset:256
	s_add_u32 s22, s22, 0x28000
	s_addc_u32 s23, s23, 0
	s_nop 1
	global_load_dwordx4 v[172:175], v196, s[22:23]
	global_load_dwordx4 v[176:179], v196, s[22:23] offset:256
	s_add_u32 s22, s22, 0x8000
	s_addc_u32 s23, s23, 0
	s_nop 1
	global_load_dwordx4 v[180:183], v196, s[22:23]
	global_load_dwordx4 v[184:187], v196, s[22:23] offset:256
	s_add_u32 s22, s22, 0x8000
	s_addc_u32 s23, s23, 0
	s_nop 1
	global_load_dwordx4 v[188:191], v196, s[22:23]
	global_load_dwordx4 v[192:195], v196, s[22:23] offset:256
	s_add_u32 s22, s22, 0x8000
	s_addc_u32 s23, s23, 0
	s_nop 1
	global_load_dwordx4 v[208:211], v196, s[22:23]
	global_load_dwordx4 v[212:215], v196, s[22:23] offset:256
	s_and_b64 vcc, exec, s[10:11]
	s_cbranch_vccz .LBB0_531
	s_barrier
.LBB0_531:
	s_lshl_b32 s22, s19, 11
	s_add_u32 s22, s14, s22
	s_addc_u32 s23, s15, 0
	s_nop 7
	s_nop 7
	v_permlane16_swap_b32_e32 v130, v126
	v_permlane16_swap_b32_e32 v131, v127
	v_permlane16_swap_b32_e32 v132, v128
	v_permlane16_swap_b32_e32 v133, v129
	v_permlane16_swap_b32_e32 v122, v118
	v_permlane16_swap_b32_e32 v123, v119
	v_permlane16_swap_b32_e32 v124, v120
	v_permlane16_swap_b32_e32 v125, v121
	v_permlane16_swap_b32_e32 v114, v110
	v_permlane16_swap_b32_e32 v115, v111
	v_permlane16_swap_b32_e32 v116, v112
	v_permlane16_swap_b32_e32 v117, v113
	v_permlane16_swap_b32_e32 v106, v102
	v_permlane16_swap_b32_e32 v107, v103
	v_permlane16_swap_b32_e32 v108, v104
	v_permlane16_swap_b32_e32 v109, v105
	v_permlane16_swap_b32_e32 v98, v90
	v_permlane16_swap_b32_e32 v99, v91
	v_permlane16_swap_b32_e32 v100, v92
	v_permlane16_swap_b32_e32 v101, v93
	v_permlane16_swap_b32_e32 v86, v82
	v_permlane16_swap_b32_e32 v87, v83
	v_permlane16_swap_b32_e32 v88, v84
	v_permlane16_swap_b32_e32 v89, v85
	v_permlane16_swap_b32_e32 v78, v74
	v_permlane16_swap_b32_e32 v79, v75
	v_permlane16_swap_b32_e32 v80, v76
	v_permlane16_swap_b32_e32 v81, v77
	v_permlane16_swap_b32_e32 v70, v66
	v_permlane16_swap_b32_e32 v71, v67
	v_permlane16_swap_b32_e32 v72, v68
	v_permlane16_swap_b32_e32 v73, v69
	v_permlane16_swap_b32_e32 v62, v58
	v_permlane16_swap_b32_e32 v63, v59
	v_permlane16_swap_b32_e32 v64, v60
	v_permlane16_swap_b32_e32 v65, v61
	v_permlane16_swap_b32_e32 v54, v50
	v_permlane16_swap_b32_e32 v55, v51
	v_permlane16_swap_b32_e32 v56, v52
	v_permlane16_swap_b32_e32 v57, v53
	v_permlane16_swap_b32_e32 v46, v42
	v_permlane16_swap_b32_e32 v47, v43
	v_permlane16_swap_b32_e32 v48, v44
	v_permlane16_swap_b32_e32 v49, v45
	v_permlane16_swap_b32_e32 v38, v34
	v_permlane16_swap_b32_e32 v39, v35
	v_permlane16_swap_b32_e32 v40, v36
	v_permlane16_swap_b32_e32 v41, v37
	v_permlane16_swap_b32_e32 v30, v26
	v_permlane16_swap_b32_e32 v31, v27
	v_permlane16_swap_b32_e32 v32, v28
	v_permlane16_swap_b32_e32 v33, v29
	v_permlane16_swap_b32_e32 v22, v18
	v_permlane16_swap_b32_e32 v23, v19
	v_permlane16_swap_b32_e32 v24, v20
	v_permlane16_swap_b32_e32 v25, v21
	v_permlane16_swap_b32_e32 v14, v10
	v_permlane16_swap_b32_e32 v15, v11
	v_permlane16_swap_b32_e32 v16, v12
	v_permlane16_swap_b32_e32 v17, v13
	v_permlane16_swap_b32_e32 v6, v2
	v_permlane16_swap_b32_e32 v7, v3
	v_permlane16_swap_b32_e32 v8, v4
	v_permlane16_swap_b32_e32 v9, v5
	s_waitcnt vmcnt(14)
	v_lshlrev_b32_e32 v244, 16, v140
	v_and_b32_e32 v245, 0xffff0000, v140
	v_pk_fma_f32 v[130:131], v[134:135], v[130:131], v[244:245]
	v_lshlrev_b32_e32 v246, 16, v141
	v_and_b32_e32 v247, 0xffff0000, v141
	v_pk_fma_f32 v[132:133], v[134:135], v[132:133], v[246:247]
	v_lshlrev_b32_e32 v248, 16, v142
	v_and_b32_e32 v249, 0xffff0000, v142
	v_pk_fma_f32 v[126:127], v[134:135], v[126:127], v[248:249]
	v_lshlrev_b32_e32 v250, 16, v143
	v_and_b32_e32 v251, 0xffff0000, v143
	v_pk_fma_f32 v[128:129], v[134:135], v[128:129], v[250:251]
	v_cvt_pk_bf16_f32 v140, v130, v131
	v_cvt_pk_bf16_f32 v141, v132, v133
	v_cvt_pk_bf16_f32 v142, v126, v127
	v_cvt_pk_bf16_f32 v143, v128, v129
	v_pk_mul_f32 v[240:241], v[130:131], v[130:131]
	global_store_dwordx4 v196, v[140:143], s[22:23]
	v_pk_fma_f32 v[240:241], v[132:133], v[132:133], v[240:241]
	v_pk_fma_f32 v[240:241], v[126:127], v[126:127], v[240:241]
	v_pk_fma_f32 v[240:241], v[128:129], v[128:129], v[240:241]
	v_lshlrev_b32_e32 v244, 16, v144
	v_and_b32_e32 v245, 0xffff0000, v144
	v_pk_fma_f32 v[122:123], v[134:135], v[122:123], v[244:245]
	v_lshlrev_b32_e32 v246, 16, v145
	v_and_b32_e32 v247, 0xffff0000, v145
	v_pk_fma_f32 v[124:125], v[134:135], v[124:125], v[246:247]
	v_lshlrev_b32_e32 v248, 16, v146
	v_and_b32_e32 v249, 0xffff0000, v146
	v_pk_fma_f32 v[118:119], v[134:135], v[118:119], v[248:249]
	v_lshlrev_b32_e32 v250, 16, v147
	v_and_b32_e32 v251, 0xffff0000, v147
	v_pk_fma_f32 v[120:121], v[134:135], v[120:121], v[250:251]
	v_cvt_pk_bf16_f32 v144, v122, v123
	v_cvt_pk_bf16_f32 v145, v124, v125
	v_cvt_pk_bf16_f32 v146, v118, v119
	v_cvt_pk_bf16_f32 v147, v120, v121
	v_pk_mul_f32 v[242:243], v[122:123], v[122:123]
	global_store_dwordx4 v196, v[144:147], s[22:23] offset:256
	v_pk_fma_f32 v[242:243], v[124:125], v[124:125], v[242:243]
	v_pk_fma_f32 v[242:243], v[118:119], v[118:119], v[242:243]
	v_pk_fma_f32 v[242:243], v[120:121], v[120:121], v[242:243]
	v_pk_add_f32 v[240:241], v[240:241], v[242:243]
	s_add_u32 s22, s22, 0x8000
	s_addc_u32 s23, s23, 0
	v_add_f32_e32 v216, v240, v241
	s_waitcnt vmcnt(14)
	v_lshlrev_b32_e32 v244, 16, v148
	v_and_b32_e32 v245, 0xffff0000, v148
	v_pk_fma_f32 v[114:115], v[134:135], v[114:115], v[244:245]
	v_lshlrev_b32_e32 v246, 16, v149
	v_and_b32_e32 v247, 0xffff0000, v149
	v_pk_fma_f32 v[116:117], v[134:135], v[116:117], v[246:247]
	v_lshlrev_b32_e32 v248, 16, v150
	v_and_b32_e32 v249, 0xffff0000, v150
	v_pk_fma_f32 v[110:111], v[134:135], v[110:111], v[248:249]
	v_lshlrev_b32_e32 v250, 16, v151
	v_and_b32_e32 v251, 0xffff0000, v151
	v_pk_fma_f32 v[112:113], v[134:135], v[112:113], v[250:251]
	v_cvt_pk_bf16_f32 v148, v114, v115
	v_cvt_pk_bf16_f32 v149, v116, v117
	v_cvt_pk_bf16_f32 v150, v110, v111
	v_cvt_pk_bf16_f32 v151, v112, v113
	v_pk_mul_f32 v[240:241], v[114:115], v[114:115]
	global_store_dwordx4 v196, v[148:151], s[22:23]
	v_pk_fma_f32 v[240:241], v[116:117], v[116:117], v[240:241]
	v_pk_fma_f32 v[240:241], v[110:111], v[110:111], v[240:241]
	v_pk_fma_f32 v[240:241], v[112:113], v[112:113], v[240:241]
	v_lshlrev_b32_e32 v244, 16, v152
	v_and_b32_e32 v245, 0xffff0000, v152
	v_pk_fma_f32 v[106:107], v[134:135], v[106:107], v[244:245]
	v_lshlrev_b32_e32 v246, 16, v153
	v_and_b32_e32 v247, 0xffff0000, v153
	v_pk_fma_f32 v[108:109], v[134:135], v[108:109], v[246:247]
	v_lshlrev_b32_e32 v248, 16, v154
	v_and_b32_e32 v249, 0xffff0000, v154
	v_pk_fma_f32 v[102:103], v[134:135], v[102:103], v[248:249]
	v_lshlrev_b32_e32 v250, 16, v155
	v_and_b32_e32 v251, 0xffff0000, v155
	v_pk_fma_f32 v[104:105], v[134:135], v[104:105], v[250:251]
	v_cvt_pk_bf16_f32 v152, v106, v107
	v_cvt_pk_bf16_f32 v153, v108, v109
	v_cvt_pk_bf16_f32 v154, v102, v103
	v_cvt_pk_bf16_f32 v155, v104, v105
	v_pk_mul_f32 v[242:243], v[106:107], v[106:107]
	global_store_dwordx4 v196, v[152:155], s[22:23] offset:256
	v_pk_fma_f32 v[242:243], v[108:109], v[108:109], v[242:243]
	v_pk_fma_f32 v[242:243], v[102:103], v[102:103], v[242:243]
	v_pk_fma_f32 v[242:243], v[104:105], v[104:105], v[242:243]
	v_pk_add_f32 v[240:241], v[240:241], v[242:243]
	s_add_u32 s22, s22, 0x8000
	s_addc_u32 s23, s23, 0
	v_add_f32_e32 v217, v240, v241
	s_waitcnt vmcnt(14)
	v_lshlrev_b32_e32 v244, 16, v156
	v_and_b32_e32 v245, 0xffff0000, v156
	v_pk_fma_f32 v[98:99], v[134:135], v[98:99], v[244:245]
	v_lshlrev_b32_e32 v246, 16, v157
	v_and_b32_e32 v247, 0xffff0000, v157
	v_pk_fma_f32 v[100:101], v[134:135], v[100:101], v[246:247]
	v_lshlrev_b32_e32 v248, 16, v158
	v_and_b32_e32 v249, 0xffff0000, v158
	v_pk_fma_f32 v[90:91], v[134:135], v[90:91], v[248:249]
	v_lshlrev_b32_e32 v250, 16, v159
	v_and_b32_e32 v251, 0xffff0000, v159
	v_pk_fma_f32 v[92:93], v[134:135], v[92:93], v[250:251]
	v_cvt_pk_bf16_f32 v156, v98, v99
	v_cvt_pk_bf16_f32 v157, v100, v101
	v_cvt_pk_bf16_f32 v158, v90, v91
	v_cvt_pk_bf16_f32 v159, v92, v93
	v_pk_mul_f32 v[240:241], v[98:99], v[98:99]
	global_store_dwordx4 v196, v[156:159], s[22:23]
	v_pk_fma_f32 v[240:241], v[100:101], v[100:101], v[240:241]
	v_pk_fma_f32 v[240:241], v[90:91], v[90:91], v[240:241]
	v_pk_fma_f32 v[240:241], v[92:93], v[92:93], v[240:241]
	v_lshlrev_b32_e32 v244, 16, v160
	v_and_b32_e32 v245, 0xffff0000, v160
	v_pk_fma_f32 v[86:87], v[134:135], v[86:87], v[244:245]
	v_lshlrev_b32_e32 v246, 16, v161
	v_and_b32_e32 v247, 0xffff0000, v161
	v_pk_fma_f32 v[88:89], v[134:135], v[88:89], v[246:247]
	v_lshlrev_b32_e32 v248, 16, v162
	v_and_b32_e32 v249, 0xffff0000, v162
	v_pk_fma_f32 v[82:83], v[134:135], v[82:83], v[248:249]
	v_lshlrev_b32_e32 v250, 16, v163
	v_and_b32_e32 v251, 0xffff0000, v163
	v_pk_fma_f32 v[84:85], v[134:135], v[84:85], v[250:251]
	v_cvt_pk_bf16_f32 v160, v86, v87
	v_cvt_pk_bf16_f32 v161, v88, v89
	v_cvt_pk_bf16_f32 v162, v82, v83
	v_cvt_pk_bf16_f32 v163, v84, v85
	v_pk_mul_f32 v[242:243], v[86:87], v[86:87]
	global_store_dwordx4 v196, v[160:163], s[22:23] offset:256
	v_pk_fma_f32 v[242:243], v[88:89], v[88:89], v[242:243]
	v_pk_fma_f32 v[242:243], v[82:83], v[82:83], v[242:243]
	v_pk_fma_f32 v[242:243], v[84:85], v[84:85], v[242:243]
	v_pk_add_f32 v[240:241], v[240:241], v[242:243]
	s_add_u32 s22, s22, 0x8000
	s_addc_u32 s23, s23, 0
	v_add_f32_e32 v218, v240, v241
	s_waitcnt vmcnt(14)
	v_lshlrev_b32_e32 v244, 16, v164
	v_and_b32_e32 v245, 0xffff0000, v164
	v_pk_fma_f32 v[78:79], v[134:135], v[78:79], v[244:245]
	v_lshlrev_b32_e32 v246, 16, v165
	v_and_b32_e32 v247, 0xffff0000, v165
	v_pk_fma_f32 v[80:81], v[134:135], v[80:81], v[246:247]
	v_lshlrev_b32_e32 v248, 16, v166
	v_and_b32_e32 v249, 0xffff0000, v166
	v_pk_fma_f32 v[74:75], v[134:135], v[74:75], v[248:249]
	v_lshlrev_b32_e32 v250, 16, v167
	v_and_b32_e32 v251, 0xffff0000, v167
	v_pk_fma_f32 v[76:77], v[134:135], v[76:77], v[250:251]
	v_cvt_pk_bf16_f32 v164, v78, v79
	v_cvt_pk_bf16_f32 v165, v80, v81
	v_cvt_pk_bf16_f32 v166, v74, v75
	v_cvt_pk_bf16_f32 v167, v76, v77
	v_pk_mul_f32 v[240:241], v[78:79], v[78:79]
	global_store_dwordx4 v196, v[164:167], s[22:23]
	v_pk_fma_f32 v[240:241], v[80:81], v[80:81], v[240:241]
	v_pk_fma_f32 v[240:241], v[74:75], v[74:75], v[240:241]
	v_pk_fma_f32 v[240:241], v[76:77], v[76:77], v[240:241]
	v_lshlrev_b32_e32 v244, 16, v168
	v_and_b32_e32 v245, 0xffff0000, v168
	v_pk_fma_f32 v[70:71], v[134:135], v[70:71], v[244:245]
	v_lshlrev_b32_e32 v246, 16, v169
	v_and_b32_e32 v247, 0xffff0000, v169
	v_pk_fma_f32 v[72:73], v[134:135], v[72:73], v[246:247]
	v_lshlrev_b32_e32 v248, 16, v170
	v_and_b32_e32 v249, 0xffff0000, v170
	v_pk_fma_f32 v[66:67], v[134:135], v[66:67], v[248:249]
	v_lshlrev_b32_e32 v250, 16, v171
	v_and_b32_e32 v251, 0xffff0000, v171
	v_pk_fma_f32 v[68:69], v[134:135], v[68:69], v[250:251]
	v_cvt_pk_bf16_f32 v168, v70, v71
	v_cvt_pk_bf16_f32 v169, v72, v73
	v_cvt_pk_bf16_f32 v170, v66, v67
	v_cvt_pk_bf16_f32 v171, v68, v69
	v_pk_mul_f32 v[242:243], v[70:71], v[70:71]
	global_store_dwordx4 v196, v[168:171], s[22:23] offset:256
	v_pk_fma_f32 v[242:243], v[72:73], v[72:73], v[242:243]
	v_pk_fma_f32 v[242:243], v[66:67], v[66:67], v[242:243]
	v_pk_fma_f32 v[242:243], v[68:69], v[68:69], v[242:243]
	v_pk_add_f32 v[240:241], v[240:241], v[242:243]
	s_add_u32 s22, s22, 0x28000
	s_addc_u32 s23, s23, 0
	v_add_f32_e32 v219, v240, v241
	s_waitcnt vmcnt(14)
	v_lshlrev_b32_e32 v244, 16, v172
	v_and_b32_e32 v245, 0xffff0000, v172
	v_pk_fma_f32 v[62:63], v[134:135], v[62:63], v[244:245]
	v_lshlrev_b32_e32 v246, 16, v173
	v_and_b32_e32 v247, 0xffff0000, v173
	v_pk_fma_f32 v[64:65], v[134:135], v[64:65], v[246:247]
	v_lshlrev_b32_e32 v248, 16, v174
	v_and_b32_e32 v249, 0xffff0000, v174
	v_pk_fma_f32 v[58:59], v[134:135], v[58:59], v[248:249]
	v_lshlrev_b32_e32 v250, 16, v175
	v_and_b32_e32 v251, 0xffff0000, v175
	v_pk_fma_f32 v[60:61], v[134:135], v[60:61], v[250:251]
	v_cvt_pk_bf16_f32 v172, v62, v63
	v_cvt_pk_bf16_f32 v173, v64, v65
	v_cvt_pk_bf16_f32 v174, v58, v59
	v_cvt_pk_bf16_f32 v175, v60, v61
	v_pk_mul_f32 v[240:241], v[62:63], v[62:63]
	global_store_dwordx4 v196, v[172:175], s[22:23]
	v_pk_fma_f32 v[240:241], v[64:65], v[64:65], v[240:241]
	v_pk_fma_f32 v[240:241], v[58:59], v[58:59], v[240:241]
	v_pk_fma_f32 v[240:241], v[60:61], v[60:61], v[240:241]
	v_lshlrev_b32_e32 v244, 16, v176
	v_and_b32_e32 v245, 0xffff0000, v176
	v_pk_fma_f32 v[54:55], v[134:135], v[54:55], v[244:245]
	v_lshlrev_b32_e32 v246, 16, v177
	v_and_b32_e32 v247, 0xffff0000, v177
	v_pk_fma_f32 v[56:57], v[134:135], v[56:57], v[246:247]
	v_lshlrev_b32_e32 v248, 16, v178
	v_and_b32_e32 v249, 0xffff0000, v178
	v_pk_fma_f32 v[50:51], v[134:135], v[50:51], v[248:249]
	v_lshlrev_b32_e32 v250, 16, v179
	v_and_b32_e32 v251, 0xffff0000, v179
	v_pk_fma_f32 v[52:53], v[134:135], v[52:53], v[250:251]
	v_cvt_pk_bf16_f32 v176, v54, v55
	v_cvt_pk_bf16_f32 v177, v56, v57
	v_cvt_pk_bf16_f32 v178, v50, v51
	v_cvt_pk_bf16_f32 v179, v52, v53
	v_pk_mul_f32 v[242:243], v[54:55], v[54:55]
	global_store_dwordx4 v196, v[176:179], s[22:23] offset:256
	v_pk_fma_f32 v[242:243], v[56:57], v[56:57], v[242:243]
	v_pk_fma_f32 v[242:243], v[50:51], v[50:51], v[242:243]
	v_pk_fma_f32 v[242:243], v[52:53], v[52:53], v[242:243]
	v_pk_add_f32 v[240:241], v[240:241], v[242:243]
	s_add_u32 s22, s22, 0x8000
	s_addc_u32 s23, s23, 0
	v_add_f32_e32 v220, v240, v241
	s_waitcnt vmcnt(14)
	v_lshlrev_b32_e32 v244, 16, v180
	v_and_b32_e32 v245, 0xffff0000, v180
	v_pk_fma_f32 v[46:47], v[134:135], v[46:47], v[244:245]
	v_lshlrev_b32_e32 v246, 16, v181
	v_and_b32_e32 v247, 0xffff0000, v181
	v_pk_fma_f32 v[48:49], v[134:135], v[48:49], v[246:247]
	v_lshlrev_b32_e32 v248, 16, v182
	v_and_b32_e32 v249, 0xffff0000, v182
	v_pk_fma_f32 v[42:43], v[134:135], v[42:43], v[248:249]
	v_lshlrev_b32_e32 v250, 16, v183
	v_and_b32_e32 v251, 0xffff0000, v183
	v_pk_fma_f32 v[44:45], v[134:135], v[44:45], v[250:251]
	v_cvt_pk_bf16_f32 v180, v46, v47
	v_cvt_pk_bf16_f32 v181, v48, v49
	v_cvt_pk_bf16_f32 v182, v42, v43
	v_cvt_pk_bf16_f32 v183, v44, v45
	v_pk_mul_f32 v[240:241], v[46:47], v[46:47]
	global_store_dwordx4 v196, v[180:183], s[22:23]
	v_pk_fma_f32 v[240:241], v[48:49], v[48:49], v[240:241]
	v_pk_fma_f32 v[240:241], v[42:43], v[42:43], v[240:241]
	v_pk_fma_f32 v[240:241], v[44:45], v[44:45], v[240:241]
	v_lshlrev_b32_e32 v244, 16, v184
	v_and_b32_e32 v245, 0xffff0000, v184
	v_pk_fma_f32 v[38:39], v[134:135], v[38:39], v[244:245]
	v_lshlrev_b32_e32 v246, 16, v185
	v_and_b32_e32 v247, 0xffff0000, v185
	v_pk_fma_f32 v[40:41], v[134:135], v[40:41], v[246:247]
	v_lshlrev_b32_e32 v248, 16, v186
	v_and_b32_e32 v249, 0xffff0000, v186
	v_pk_fma_f32 v[34:35], v[134:135], v[34:35], v[248:249]
	v_lshlrev_b32_e32 v250, 16, v187
	v_and_b32_e32 v251, 0xffff0000, v187
	v_pk_fma_f32 v[36:37], v[134:135], v[36:37], v[250:251]
	v_cvt_pk_bf16_f32 v184, v38, v39
	v_cvt_pk_bf16_f32 v185, v40, v41
	v_cvt_pk_bf16_f32 v186, v34, v35
	v_cvt_pk_bf16_f32 v187, v36, v37
	v_pk_mul_f32 v[242:243], v[38:39], v[38:39]
	global_store_dwordx4 v196, v[184:187], s[22:23] offset:256
	v_pk_fma_f32 v[242:243], v[40:41], v[40:41], v[242:243]
	v_pk_fma_f32 v[242:243], v[34:35], v[34:35], v[242:243]
	v_pk_fma_f32 v[242:243], v[36:37], v[36:37], v[242:243]
	v_pk_add_f32 v[240:241], v[240:241], v[242:243]
	s_add_u32 s22, s22, 0x8000
	s_addc_u32 s23, s23, 0
	v_add_f32_e32 v221, v240, v241
	s_waitcnt vmcnt(14)
	v_lshlrev_b32_e32 v244, 16, v188
	v_and_b32_e32 v245, 0xffff0000, v188
	v_pk_fma_f32 v[30:31], v[134:135], v[30:31], v[244:245]
	v_lshlrev_b32_e32 v246, 16, v189
	v_and_b32_e32 v247, 0xffff0000, v189
	v_pk_fma_f32 v[32:33], v[134:135], v[32:33], v[246:247]
	v_lshlrev_b32_e32 v248, 16, v190
	v_and_b32_e32 v249, 0xffff0000, v190
	v_pk_fma_f32 v[26:27], v[134:135], v[26:27], v[248:249]
	v_lshlrev_b32_e32 v250, 16, v191
	v_and_b32_e32 v251, 0xffff0000, v191
	v_pk_fma_f32 v[28:29], v[134:135], v[28:29], v[250:251]
	v_cvt_pk_bf16_f32 v188, v30, v31
	v_cvt_pk_bf16_f32 v189, v32, v33
	v_cvt_pk_bf16_f32 v190, v26, v27
	v_cvt_pk_bf16_f32 v191, v28, v29
	v_pk_mul_f32 v[240:241], v[30:31], v[30:31]
	global_store_dwordx4 v196, v[188:191], s[22:23]
	v_pk_fma_f32 v[240:241], v[32:33], v[32:33], v[240:241]
	v_pk_fma_f32 v[240:241], v[26:27], v[26:27], v[240:241]
	v_pk_fma_f32 v[240:241], v[28:29], v[28:29], v[240:241]
	v_lshlrev_b32_e32 v244, 16, v192
	v_and_b32_e32 v245, 0xffff0000, v192
	v_pk_fma_f32 v[22:23], v[134:135], v[22:23], v[244:245]
	v_lshlrev_b32_e32 v246, 16, v193
	v_and_b32_e32 v247, 0xffff0000, v193
	v_pk_fma_f32 v[24:25], v[134:135], v[24:25], v[246:247]
	v_lshlrev_b32_e32 v248, 16, v194
	v_and_b32_e32 v249, 0xffff0000, v194
	v_pk_fma_f32 v[18:19], v[134:135], v[18:19], v[248:249]
	v_lshlrev_b32_e32 v250, 16, v195
	v_and_b32_e32 v251, 0xffff0000, v195
	v_pk_fma_f32 v[20:21], v[134:135], v[20:21], v[250:251]
	v_cvt_pk_bf16_f32 v192, v22, v23
	v_cvt_pk_bf16_f32 v193, v24, v25
	v_cvt_pk_bf16_f32 v194, v18, v19
	v_cvt_pk_bf16_f32 v195, v20, v21
	v_pk_mul_f32 v[242:243], v[22:23], v[22:23]
	global_store_dwordx4 v196, v[192:195], s[22:23] offset:256
	v_pk_fma_f32 v[242:243], v[24:25], v[24:25], v[242:243]
	v_pk_fma_f32 v[242:243], v[18:19], v[18:19], v[242:243]
	v_pk_fma_f32 v[242:243], v[20:21], v[20:21], v[242:243]
	v_pk_add_f32 v[240:241], v[240:241], v[242:243]
	s_add_u32 s22, s22, 0x8000
	s_addc_u32 s23, s23, 0
	v_add_f32_e32 v202, v240, v241
	s_waitcnt vmcnt(14)
	v_lshlrev_b32_e32 v244, 16, v208
	v_and_b32_e32 v245, 0xffff0000, v208
	v_pk_fma_f32 v[14:15], v[134:135], v[14:15], v[244:245]
	v_lshlrev_b32_e32 v246, 16, v209
	v_and_b32_e32 v247, 0xffff0000, v209
	v_pk_fma_f32 v[16:17], v[134:135], v[16:17], v[246:247]
	v_lshlrev_b32_e32 v248, 16, v210
	v_and_b32_e32 v249, 0xffff0000, v210
	v_pk_fma_f32 v[10:11], v[134:135], v[10:11], v[248:249]
	v_lshlrev_b32_e32 v250, 16, v211
	v_and_b32_e32 v251, 0xffff0000, v211
	v_pk_fma_f32 v[12:13], v[134:135], v[12:13], v[250:251]
	v_cvt_pk_bf16_f32 v208, v14, v15
	v_cvt_pk_bf16_f32 v209, v16, v17
	v_cvt_pk_bf16_f32 v210, v10, v11
	v_cvt_pk_bf16_f32 v211, v12, v13
	v_pk_mul_f32 v[240:241], v[14:15], v[14:15]
	global_store_dwordx4 v196, v[208:211], s[22:23]
	v_pk_fma_f32 v[240:241], v[16:17], v[16:17], v[240:241]
	v_pk_fma_f32 v[240:241], v[10:11], v[10:11], v[240:241]
	v_pk_fma_f32 v[240:241], v[12:13], v[12:13], v[240:241]
	v_lshlrev_b32_e32 v244, 16, v212
	v_and_b32_e32 v245, 0xffff0000, v212
	v_pk_fma_f32 v[6:7], v[134:135], v[6:7], v[244:245]
	v_lshlrev_b32_e32 v246, 16, v213
	v_and_b32_e32 v247, 0xffff0000, v213
	v_pk_fma_f32 v[8:9], v[134:135], v[8:9], v[246:247]
	v_lshlrev_b32_e32 v248, 16, v214
	v_and_b32_e32 v249, 0xffff0000, v214
	v_pk_fma_f32 v[2:3], v[134:135], v[2:3], v[248:249]
	v_lshlrev_b32_e32 v250, 16, v215
	v_and_b32_e32 v251, 0xffff0000, v215
	v_pk_fma_f32 v[4:5], v[134:135], v[4:5], v[250:251]
	v_cvt_pk_bf16_f32 v212, v6, v7
	v_cvt_pk_bf16_f32 v213, v8, v9
	v_cvt_pk_bf16_f32 v214, v2, v3
	v_cvt_pk_bf16_f32 v215, v4, v5
	v_pk_mul_f32 v[242:243], v[6:7], v[6:7]
	global_store_dwordx4 v196, v[212:215], s[22:23] offset:256
	v_pk_fma_f32 v[242:243], v[8:9], v[8:9], v[242:243]
	v_pk_fma_f32 v[242:243], v[2:3], v[2:3], v[242:243]
	v_pk_fma_f32 v[242:243], v[4:5], v[4:5], v[242:243]
	v_pk_add_f32 v[240:241], v[240:241], v[242:243]
	v_add_f32_e32 v203, v240, v241
	v_mov_b32_e32 v244, v216
	v_mov_b32_e32 v245, v217
	v_mov_b32_e32 v246, v218
	v_mov_b32_e32 v247, v219
	v_mov_b32_e32 v248, v220
	v_mov_b32_e32 v249, v221
	v_mov_b32_e32 v250, v202
	v_mov_b32_e32 v251, v203
	s_nop 1
	v_permlane16_swap_b32_e32 v216, v244
	v_permlane16_swap_b32_e32 v217, v245
	v_permlane16_swap_b32_e32 v218, v246
	v_permlane16_swap_b32_e32 v219, v247
	v_permlane16_swap_b32_e32 v220, v248
	v_permlane16_swap_b32_e32 v221, v249
	v_permlane16_swap_b32_e32 v202, v250
	v_permlane16_swap_b32_e32 v203, v251
	v_add_f32_e32 v216, v216, v244
	v_add_f32_e32 v217, v217, v245
	v_add_f32_e32 v218, v218, v246
	v_add_f32_e32 v219, v219, v247
	v_add_f32_e32 v220, v220, v248
	v_add_f32_e32 v221, v221, v249
	v_add_f32_e32 v202, v202, v250
	v_add_f32_e32 v203, v203, v251
	v_mov_b32_e32 v244, v216
	v_mov_b32_e32 v245, v217
	v_mov_b32_e32 v246, v218
	v_mov_b32_e32 v247, v219
	v_mov_b32_e32 v248, v220
	v_mov_b32_e32 v249, v221
	v_mov_b32_e32 v250, v202
	v_mov_b32_e32 v251, v203
	s_nop 1
	v_permlane32_swap_b32_e32 v216, v244
	v_permlane32_swap_b32_e32 v217, v245
	v_permlane32_swap_b32_e32 v218, v246
	v_permlane32_swap_b32_e32 v219, v247
	v_permlane32_swap_b32_e32 v220, v248
	v_permlane32_swap_b32_e32 v221, v249
	v_permlane32_swap_b32_e32 v202, v250
	v_permlane32_swap_b32_e32 v203, v251
	v_add_f32_e32 v216, v216, v244
	v_add_f32_e32 v217, v217, v245
	v_add_f32_e32 v218, v218, v246
	v_add_f32_e32 v219, v219, v247
	v_add_f32_e32 v220, v220, v248
	v_add_f32_e32 v221, v221, v249
	v_add_f32_e32 v202, v202, v250
	v_add_f32_e32 v203, v203, v251
	s_and_saveexec_b64 s[22:23], s[36:37]
	ds_write_b32 v235, v216
	ds_write_b32 v235, v217 offset:256
	ds_write_b32 v235, v218 offset:512
	ds_write_b32 v235, v219 offset:768
	ds_write_b32 v235, v220 offset:2048
	ds_write_b32 v235, v221 offset:2304
	ds_write_b32 v235, v202 offset:2560
	ds_write_b32 v235, v203 offset:2816

.LBB0_565:
	s_add_u32 s40, s38, 0xfffc0080
	s_addc_u32 s41, s39, -1
	s_add_i32 s52, 0, 0x10000
	s_cmp_eq_u32 s51, 12
	s_cselect_b32 s43, s21, s41
	s_cselect_b32 s42, s47, s40
	v_add_u32_e32 v0, s52, v141
	s_cselect_b32 s41, s19, s50
	s_cselect_b32 s40, s48, s49
	s_add_i32 s54, 0, 0x14000
	ds_read_b128 v[146:149], v0
	ds_read_b128 v[150:153], v0 offset:1024
	ds_read_b128 v[154:157], v0 offset:2048
	ds_read_b128 v[158:161], v0 offset:3072
	v_add_u32_e32 v0, s54, v141
	ds_read_b128 v[162:165], v0
	ds_read_b128 v[166:169], v0 offset:1024
	ds_read_b128 v[170:173], v0 offset:2048
	ds_read_b128 v[174:177], v0 offset:3072
	s_add_i32 m0, s8, 0xc000
	ds_read_b128 v[178:181], v145
	ds_read_b128 v[182:185], v145 offset:1024
	ds_read_b128 v[186:189], v145 offset:2048
	ds_read_b128 v[190:193], v145 offset:3072
	ds_read_b128 v[194:197], v145 offset:4096
	ds_read_b128 v[208:211], v145 offset:5120
	ds_read_b128 v[212:215], v145 offset:6144
	ds_read_b128 v[216:219], v145 offset:7168
	global_load_lds_dwordx4 v138, s[38:39]
	s_add_i32 m0, s8, 0xe000
	s_nop 0
	global_load_lds_dwordx4 v136, s[38:39]
	s_waitcnt vmcnt(8)
	s_waitcnt lgkmcnt(0)
	s_barrier
	s_setprio 1
	s_waitcnt lgkmcnt(0)
	v_mfma_f32_16x16x32_bf16 v[130:133], v[146:149], v[178:181], v[130:133]
	v_mfma_f32_16x16x32_bf16 v[126:129], v[154:157], v[178:181], v[126:129]
	v_mfma_f32_16x16x32_bf16 v[114:117], v[146:149], v[186:189], v[114:117]
	v_mfma_f32_16x16x32_bf16 v[110:113], v[154:157], v[186:189], v[110:113]
	v_mfma_f32_16x16x32_bf16 v[98:101], v[146:149], v[194:197], v[98:101]
	v_mfma_f32_16x16x32_bf16 v[90:93], v[154:157], v[194:197], v[90:93]
	v_mfma_f32_16x16x32_bf16 v[78:81], v[146:149], v[212:215], v[78:81]
	v_mfma_f32_16x16x32_bf16 v[74:77], v[154:157], v[212:215], v[74:77]
	v_mfma_f32_16x16x32_bf16 v[130:133], v[150:153], v[182:185], v[130:133]
	v_mfma_f32_16x16x32_bf16 v[126:129], v[158:161], v[182:185], v[126:129]
	v_mfma_f32_16x16x32_bf16 v[114:117], v[150:153], v[190:193], v[114:117]
	v_mfma_f32_16x16x32_bf16 v[110:113], v[158:161], v[190:193], v[110:113]
	v_mfma_f32_16x16x32_bf16 v[98:101], v[150:153], v[208:211], v[98:101]
	v_mfma_f32_16x16x32_bf16 v[90:93], v[158:161], v[208:211], v[90:93]
	v_mfma_f32_16x16x32_bf16 v[78:81], v[150:153], v[216:219], v[78:81]
	v_mfma_f32_16x16x32_bf16 v[74:77], v[158:161], v[216:219], v[74:77]
	s_setprio 0
	s_setprio 1
	v_mfma_f32_16x16x32_bf16 v[122:125], v[162:165], v[178:181], v[122:125]
	v_mfma_f32_16x16x32_bf16 v[118:121], v[170:173], v[178:181], v[118:121]
	v_mfma_f32_16x16x32_bf16 v[106:109], v[162:165], v[186:189], v[106:109]
	v_mfma_f32_16x16x32_bf16 v[102:105], v[170:173], v[186:189], v[102:105]
	v_mfma_f32_16x16x32_bf16 v[86:89], v[162:165], v[194:197], v[86:89]
	v_mfma_f32_16x16x32_bf16 v[82:85], v[170:173], v[194:197], v[82:85]
	v_mfma_f32_16x16x32_bf16 v[70:73], v[162:165], v[212:215], v[70:73]
	v_mfma_f32_16x16x32_bf16 v[66:69], v[170:173], v[212:215], v[66:69]
	v_mfma_f32_16x16x32_bf16 v[122:125], v[166:169], v[182:185], v[122:125]
	v_mfma_f32_16x16x32_bf16 v[118:121], v[174:177], v[182:185], v[118:121]
	v_mfma_f32_16x16x32_bf16 v[106:109], v[166:169], v[190:193], v[106:109]
	v_mfma_f32_16x16x32_bf16 v[102:105], v[174:177], v[190:193], v[102:105]
	v_mfma_f32_16x16x32_bf16 v[86:89], v[166:169], v[208:211], v[86:89]
	v_mfma_f32_16x16x32_bf16 v[82:85], v[174:177], v[208:211], v[82:85]
	v_mfma_f32_16x16x32_bf16 v[70:73], v[166:169], v[216:219], v[70:73]
	v_mfma_f32_16x16x32_bf16 v[66:69], v[174:177], v[216:219], v[66:69]
	s_setprio 0
	s_barrier
	s_add_i32 s52, s52, s6
	s_mov_b32 m0, s52
	ds_read_b128 v[178:181], v145 offset:16384
	ds_read_b128 v[182:185], v145 offset:17408
	ds_read_b128 v[186:189], v145 offset:18432
	ds_read_b128 v[190:193], v145 offset:19456
	ds_read_b128 v[194:197], v145 offset:20480
	ds_read_b128 v[208:211], v145 offset:21504
	ds_read_b128 v[212:215], v145 offset:22528
	ds_read_b128 v[216:219], v145 offset:23552
	global_load_lds_dwordx4 v134, s[40:41]
	s_add_i32 m0, s52, 0x2000
	s_add_u32 s52, s40, 0x40000
	s_addc_u32 s53, s41, 0
	s_add_i32 s54, s54, s6
	global_load_lds_dwordx4 v94, s[40:41]
	s_mov_b32 m0, s54
	s_nop 0
	global_load_lds_dwordx4 v134, s[52:53]
	s_add_i32 m0, s54, 0x2000
	s_nop 0
	global_load_lds_dwordx4 v94, s[52:53]
	s_mov_b32 m0, s8
	s_nop 0
	global_load_lds_dwordx4 v134, s[42:43]
	s_mov_b32 m0, s9
	s_nop 0
	global_load_lds_dwordx4 v94, s[42:43]
	s_waitcnt vmcnt(8)
	s_waitcnt lgkmcnt(0)
	s_barrier
	s_setprio 1
	s_waitcnt lgkmcnt(0)
	v_mfma_f32_16x16x32_bf16 v[62:65], v[146:149], v[178:181], v[62:65]
	v_mfma_f32_16x16x32_bf16 v[58:61], v[154:157], v[178:181], v[58:61]
	v_mfma_f32_16x16x32_bf16 v[46:49], v[146:149], v[186:189], v[46:49]
	v_mfma_f32_16x16x32_bf16 v[42:45], v[154:157], v[186:189], v[42:45]
	v_mfma_f32_16x16x32_bf16 v[30:33], v[146:149], v[194:197], v[30:33]
	v_mfma_f32_16x16x32_bf16 v[26:29], v[154:157], v[194:197], v[26:29]
	v_mfma_f32_16x16x32_bf16 v[14:17], v[146:149], v[212:215], v[14:17]
	v_mfma_f32_16x16x32_bf16 v[10:13], v[154:157], v[212:215], v[10:13]
	v_mfma_f32_16x16x32_bf16 v[62:65], v[150:153], v[182:185], v[62:65]
	v_mfma_f32_16x16x32_bf16 v[58:61], v[158:161], v[182:185], v[58:61]
	v_mfma_f32_16x16x32_bf16 v[46:49], v[150:153], v[190:193], v[46:49]
	v_mfma_f32_16x16x32_bf16 v[42:45], v[158:161], v[190:193], v[42:45]
	v_mfma_f32_16x16x32_bf16 v[30:33], v[150:153], v[208:211], v[30:33]
	v_mfma_f32_16x16x32_bf16 v[26:29], v[158:161], v[208:211], v[26:29]
	v_mfma_f32_16x16x32_bf16 v[14:17], v[150:153], v[216:219], v[14:17]
	v_mfma_f32_16x16x32_bf16 v[10:13], v[158:161], v[216:219], v[10:13]
	s_setprio 0
	s_setprio 1
	v_mfma_f32_16x16x32_bf16 v[54:57], v[162:165], v[178:181], v[54:57]
	v_mfma_f32_16x16x32_bf16 v[50:53], v[170:173], v[178:181], v[50:53]
	v_mfma_f32_16x16x32_bf16 v[38:41], v[162:165], v[186:189], v[38:41]
	v_mfma_f32_16x16x32_bf16 v[34:37], v[170:173], v[186:189], v[34:37]
	v_mfma_f32_16x16x32_bf16 v[22:25], v[162:165], v[194:197], v[22:25]
	v_mfma_f32_16x16x32_bf16 v[18:21], v[170:173], v[194:197], v[18:21]
	v_mfma_f32_16x16x32_bf16 v[6:9], v[162:165], v[212:215], v[6:9]
	v_mfma_f32_16x16x32_bf16 v[2:5], v[170:173], v[212:215], v[2:5]
	v_mfma_f32_16x16x32_bf16 v[54:57], v[166:169], v[182:185], v[54:57]
	v_mfma_f32_16x16x32_bf16 v[50:53], v[174:177], v[182:185], v[50:53]
	v_mfma_f32_16x16x32_bf16 v[38:41], v[166:169], v[190:193], v[38:41]
	v_mfma_f32_16x16x32_bf16 v[34:37], v[174:177], v[190:193], v[34:37]
	v_mfma_f32_16x16x32_bf16 v[22:25], v[166:169], v[208:211], v[22:25]
	v_mfma_f32_16x16x32_bf16 v[18:21], v[174:177], v[208:211], v[18:21]
	v_mfma_f32_16x16x32_bf16 v[6:9], v[166:169], v[216:219], v[6:9]
	v_mfma_f32_16x16x32_bf16 v[2:5], v[174:177], v[216:219], v[2:5]
	s_setprio 0
	s_barrier
	s_add_i32 s52, 0, 0x18000
	v_add_u32_e32 v0, s52, v141
	s_add_i32 s53, 0, 0x1c000
	ds_read_b128 v[146:149], v0
	ds_read_b128 v[150:153], v0 offset:1024
	ds_read_b128 v[154:157], v0 offset:2048
	ds_read_b128 v[158:161], v0 offset:3072
	v_add_u32_e32 v0, s53, v141
	ds_read_b128 v[162:165], v0
	ds_read_b128 v[166:169], v0 offset:1024
	ds_read_b128 v[170:173], v0 offset:2048
	ds_read_b128 v[174:177], v0 offset:3072
	s_add_u32 s42, s42, 0x40000
	s_addc_u32 s43, s43, 0
	s_mov_b32 m0, s12
	ds_read_b128 v[178:181], v145 offset:32768
	ds_read_b128 v[182:185], v145 offset:33792
	ds_read_b128 v[186:189], v145 offset:34816
	ds_read_b128 v[190:193], v145 offset:35840
	ds_read_b128 v[194:197], v145 offset:36864
	ds_read_b128 v[208:211], v145 offset:37888
	ds_read_b128 v[212:215], v145 offset:38912
	ds_read_b128 v[216:219], v145 offset:39936
	global_load_lds_dwordx4 v134, s[42:43]
	s_mov_b32 m0, s13
	s_nop 0
	global_load_lds_dwordx4 v94, s[42:43]
	s_waitcnt vmcnt(8)
	s_waitcnt lgkmcnt(0)
	s_barrier
	s_setprio 1
	s_waitcnt lgkmcnt(0)
	v_mfma_f32_16x16x32_bf16 v[130:133], v[146:149], v[178:181], v[130:133]
	v_mfma_f32_16x16x32_bf16 v[126:129], v[154:157], v[178:181], v[126:129]
	v_mfma_f32_16x16x32_bf16 v[114:117], v[146:149], v[186:189], v[114:117]
	v_mfma_f32_16x16x32_bf16 v[110:113], v[154:157], v[186:189], v[110:113]
	v_mfma_f32_16x16x32_bf16 v[98:101], v[146:149], v[194:197], v[98:101]
	v_mfma_f32_16x16x32_bf16 v[90:93], v[154:157], v[194:197], v[90:93]
	v_mfma_f32_16x16x32_bf16 v[78:81], v[146:149], v[212:215], v[78:81]
	v_mfma_f32_16x16x32_bf16 v[74:77], v[154:157], v[212:215], v[74:77]
	v_mfma_f32_16x16x32_bf16 v[130:133], v[150:153], v[182:185], v[130:133]
	v_mfma_f32_16x16x32_bf16 v[126:129], v[158:161], v[182:185], v[126:129]
	v_mfma_f32_16x16x32_bf16 v[114:117], v[150:153], v[190:193], v[114:117]
	v_mfma_f32_16x16x32_bf16 v[110:113], v[158:161], v[190:193], v[110:113]
	v_mfma_f32_16x16x32_bf16 v[98:101], v[150:153], v[208:211], v[98:101]
	v_mfma_f32_16x16x32_bf16 v[90:93], v[158:161], v[208:211], v[90:93]
	v_mfma_f32_16x16x32_bf16 v[78:81], v[150:153], v[216:219], v[78:81]
	v_mfma_f32_16x16x32_bf16 v[74:77], v[158:161], v[216:219], v[74:77]
	s_setprio 0
	s_setprio 1
	v_mfma_f32_16x16x32_bf16 v[122:125], v[162:165], v[178:181], v[122:125]
	v_mfma_f32_16x16x32_bf16 v[118:121], v[170:173], v[178:181], v[118:121]
	v_mfma_f32_16x16x32_bf16 v[106:109], v[162:165], v[186:189], v[106:109]
	v_mfma_f32_16x16x32_bf16 v[102:105], v[170:173], v[186:189], v[102:105]
	v_mfma_f32_16x16x32_bf16 v[86:89], v[162:165], v[194:197], v[86:89]
	v_mfma_f32_16x16x32_bf16 v[82:85], v[170:173], v[194:197], v[82:85]
	v_mfma_f32_16x16x32_bf16 v[70:73], v[162:165], v[212:215], v[70:73]
	v_mfma_f32_16x16x32_bf16 v[66:69], v[170:173], v[212:215], v[66:69]
	v_mfma_f32_16x16x32_bf16 v[122:125], v[166:169], v[182:185], v[122:125]
	v_mfma_f32_16x16x32_bf16 v[118:121], v[174:177], v[182:185], v[118:121]
	v_mfma_f32_16x16x32_bf16 v[106:109], v[166:169], v[190:193], v[106:109]
	v_mfma_f32_16x16x32_bf16 v[102:105], v[174:177], v[190:193], v[102:105]
	v_mfma_f32_16x16x32_bf16 v[86:89], v[166:169], v[208:211], v[86:89]
	v_mfma_f32_16x16x32_bf16 v[82:85], v[174:177], v[208:211], v[82:85]
	v_mfma_f32_16x16x32_bf16 v[70:73], v[166:169], v[216:219], v[70:73]
	v_mfma_f32_16x16x32_bf16 v[66:69], v[174:177], v[216:219], v[66:69]
	s_setprio 0
	s_barrier
	s_add_i32 s54, s52, s6
	s_add_i32 m0, s54, 0xffffff80
	ds_read_b128 v[178:181], v145 offset:49152
	ds_read_b128 v[182:185], v145 offset:50176
	ds_read_b128 v[186:189], v145 offset:51200
	ds_read_b128 v[190:193], v145 offset:52224
	ds_read_b128 v[194:197], v145 offset:53248
	ds_read_b128 v[208:211], v145 offset:54272
	ds_read_b128 v[212:215], v145 offset:55296
	ds_read_b128 v[216:219], v145 offset:56320
	global_load_lds_dwordx4 v134, s[40:41] offset:128
	s_add_i32 m0, s54, 0x1f80
	s_nop 0
	global_load_lds_dwordx4 v94, s[40:41] offset:128
	s_add_i32 s54, s53, s6
	s_add_u32 s40, s40, 0x40080
	s_addc_u32 s41, s41, 0
	s_mov_b32 m0, s54
	s_nop 0
	global_load_lds_dwordx4 v134, s[40:41]
	s_add_i32 m0, s54, 0x2000
	s_nop 0
	global_load_lds_dwordx4 v94, s[40:41]
	s_add_u32 s42, s42, 0xfffc0080
	s_addc_u32 s43, s43, -1
	s_mov_b32 m0, s28
	s_nop 0
	global_load_lds_dwordx4 v134, s[42:43]
	s_mov_b32 m0, s29
	s_nop 0
	global_load_lds_dwordx4 v94, s[42:43]
	s_waitcnt vmcnt(8)
	s_waitcnt lgkmcnt(0)
	s_barrier
	s_setprio 1
	s_waitcnt lgkmcnt(0)
	v_mfma_f32_16x16x32_bf16 v[62:65], v[146:149], v[178:181], v[62:65]
	v_mfma_f32_16x16x32_bf16 v[58:61], v[154:157], v[178:181], v[58:61]
	v_mfma_f32_16x16x32_bf16 v[46:49], v[146:149], v[186:189], v[46:49]
	v_mfma_f32_16x16x32_bf16 v[42:45], v[154:157], v[186:189], v[42:45]
	v_mfma_f32_16x16x32_bf16 v[30:33], v[146:149], v[194:197], v[30:33]
	v_mfma_f32_16x16x32_bf16 v[26:29], v[154:157], v[194:197], v[26:29]
	v_mfma_f32_16x16x32_bf16 v[14:17], v[146:149], v[212:215], v[14:17]
	v_mfma_f32_16x16x32_bf16 v[10:13], v[154:157], v[212:215], v[10:13]
	v_mfma_f32_16x16x32_bf16 v[62:65], v[150:153], v[182:185], v[62:65]
	v_mfma_f32_16x16x32_bf16 v[58:61], v[158:161], v[182:185], v[58:61]
	v_mfma_f32_16x16x32_bf16 v[46:49], v[150:153], v[190:193], v[46:49]
	v_mfma_f32_16x16x32_bf16 v[42:45], v[158:161], v[190:193], v[42:45]
	v_mfma_f32_16x16x32_bf16 v[30:33], v[150:153], v[208:211], v[30:33]
	v_mfma_f32_16x16x32_bf16 v[26:29], v[158:161], v[208:211], v[26:29]
	v_mfma_f32_16x16x32_bf16 v[14:17], v[150:153], v[216:219], v[14:17]
	v_mfma_f32_16x16x32_bf16 v[10:13], v[158:161], v[216:219], v[10:13]
	s_setprio 0
	s_setprio 1
	v_mfma_f32_16x16x32_bf16 v[54:57], v[162:165], v[178:181], v[54:57]
	v_mfma_f32_16x16x32_bf16 v[50:53], v[170:173], v[178:181], v[50:53]
	v_mfma_f32_16x16x32_bf16 v[38:41], v[162:165], v[186:189], v[38:41]
	v_mfma_f32_16x16x32_bf16 v[34:37], v[170:173], v[186:189], v[34:37]
	v_mfma_f32_16x16x32_bf16 v[22:25], v[162:165], v[194:197], v[22:25]
	v_mfma_f32_16x16x32_bf16 v[18:21], v[170:173], v[194:197], v[18:21]
	v_mfma_f32_16x16x32_bf16 v[6:9], v[162:165], v[212:215], v[6:9]
	v_mfma_f32_16x16x32_bf16 v[2:5], v[170:173], v[212:215], v[2:5]
	v_mfma_f32_16x16x32_bf16 v[54:57], v[166:169], v[182:185], v[54:57]
	v_mfma_f32_16x16x32_bf16 v[50:53], v[174:177], v[182:185], v[50:53]
	v_mfma_f32_16x16x32_bf16 v[38:41], v[166:169], v[190:193], v[38:41]
	v_mfma_f32_16x16x32_bf16 v[34:37], v[174:177], v[190:193], v[34:37]
	v_mfma_f32_16x16x32_bf16 v[22:25], v[166:169], v[208:211], v[22:25]
	v_mfma_f32_16x16x32_bf16 v[18:21], v[174:177], v[208:211], v[18:21]
	v_mfma_f32_16x16x32_bf16 v[6:9], v[166:169], v[216:219], v[6:9]
	v_mfma_f32_16x16x32_bf16 v[2:5], v[174:177], v[216:219], v[2:5]
	s_setprio 0
	s_barrier
	s_add_i32 s51, s51, 2
	s_add_u32 s49, s49, 0x100
	s_addc_u32 s50, s50, 0
	s_add_u32 s38, s38, 0x100
	s_addc_u32 s39, s39, 0
	s_cmp_gt_u32 s51, 13
	s_cbranch_scc0 .LBB0_565
	s_lshl_b32 s19, s46, 8
	s_add_i32 s19, s19, s25
	v_or_b32_e32 v146, s19, v97
	v_or_b32_e32 v148, 16, v146
	v_or_b32_e32 v150, 32, v146
	v_ashrrev_i32_e32 v149, 31, v148
	v_ashrrev_i32_e32 v151, 31, v150
	v_lshl_add_u64 v[148:149], v[148:149], 4, s[16:17]
	v_lshl_add_u64 v[156:157], v[150:151], 4, s[16:17]
	global_load_dwordx4 v[150:153], v[148:149], off
	s_nop 0
	global_load_dwordx4 v[156:159], v[156:157], off
	v_or_b32_e32 v148, 48, v146
	v_ashrrev_i32_e32 v149, 31, v148
	v_lshl_add_u64 v[160:161], v[148:149], 4, s[16:17]
	v_add_u32_e32 v148, 0x80, v146
	v_ashrrev_i32_e32 v147, 31, v146
	v_ashrrev_i32_e32 v149, 31, v148
	v_lshl_add_u64 v[154:155], v[146:147], 4, s[16:17]
	v_lshl_add_u64 v[146:147], v[148:149], 4, s[16:17]
	global_load_dwordx4 v[160:163], v[160:161], off
	s_nop 0
	global_load_dwordx4 v[164:167], v[146:147], off
	global_load_dwordx4 v[168:171], v[154:155], off
	global_load_dwordx4 v[172:175], v[154:155], off offset:2304
	global_load_dwordx4 v[176:179], v[154:155], off offset:2560
	global_load_dwordx4 v[180:183], v[154:155], off offset:2816
	v_lshl_or_b32 v184, s45, 7, v143
	s_and_b64 vcc, exec, s[10:11]
	s_cbranch_vccz .LBB0_568
	s_barrier
.LBB0_568:
	s_waitcnt vmcnt(0)
	v_mov_b32_e32 v146, v169
	v_mov_b32_e32 v147, v170
	v_mov_b32_e32 v169, v171
	v_pk_add_f32 v[146:147], v[146:147], v[168:169]
	s_ashr_i32 s21, s19, 11
	v_add_f32_e32 v0, v146, v147
	v_mov_b32_e32 v146, v151
	v_mov_b32_e32 v147, v152
	v_mov_b32_e32 v151, v153
	v_pk_add_f32 v[146:147], v[146:147], v[150:151]
	v_fmamk_f32 v0, v0, 0x3a800000, v222
	v_add_f32_e32 v140, v146, v147
	v_mov_b32_e32 v146, v157
	v_mov_b32_e32 v147, v158
	v_mov_b32_e32 v157, v159
	v_rsq_f32_e32 v0, v0
	v_fmamk_f32 v140, v140, 0x3a800000, v222
	v_pk_add_f32 v[146:147], v[146:147], v[156:157]
	v_rsq_f32_e32 v154, v140
	v_add_f32_e32 v140, v146, v147
	v_mov_b32_e32 v146, v161
	v_mov_b32_e32 v147, v162
	v_mov_b32_e32 v161, v163
	v_fmamk_f32 v140, v140, 0x3a800000, v222
	v_pk_add_f32 v[146:147], v[146:147], v[160:161]
	v_rsq_f32_e32 v152, v140
	v_add_f32_e32 v140, v146, v147
	v_mov_b32_e32 v146, v165
	v_mov_b32_e32 v147, v166
	v_mov_b32_e32 v165, v167
	v_fmamk_f32 v140, v140, 0x3a800000, v222
	v_pk_add_f32 v[146:147], v[146:147], v[164:165]
	v_pk_mul_f32 v[130:131], v[130:131], v[0:1] op_sel_hi:[1,0]
	v_rsq_f32_e32 v150, v140
	v_add_f32_e32 v140, v146, v147
	v_mov_b32_e32 v156, v173
	v_mov_b32_e32 v157, v174
	v_mov_b32_e32 v173, v175
	v_mul_f32_e32 v151, 0xbfb8aa3b, v131
	v_fmamk_f32 v140, v140, 0x3a800000, v222
	v_pk_add_f32 v[156:157], v[156:157], v[172:173]
	v_mul_f32_e32 v147, 0xbfb8aa3b, v130
	v_exp_f32_e32 v151, v151
	v_rsq_f32_e32 v146, v140
	v_add_f32_e32 v140, v156, v157
	v_mov_b32_e32 v156, v177
	v_mov_b32_e32 v157, v178
	v_mov_b32_e32 v177, v179
	v_exp_f32_e32 v147, v147
	v_fmamk_f32 v140, v140, 0x3a800000, v222
	v_pk_add_f32 v[156:157], v[156:157], v[176:177]
	v_rsq_f32_e32 v144, v140
	v_add_f32_e32 v140, v156, v157
	v_mov_b32_e32 v156, v181
	v_mov_b32_e32 v157, v182
	v_mov_b32_e32 v181, v183
	v_pk_mul_f32 v[122:123], v[122:123], v[0:1] op_sel_hi:[1,0]
	v_fmamk_f32 v140, v140, 0x3a800000, v222
	v_pk_add_f32 v[156:157], v[156:157], v[180:181]
	v_pk_mul_f32 v[122:123], v[130:131], v[122:123]
	v_add_f32_e32 v130, 1.0, v151
	v_rsq_f32_e32 v142, v140
	v_add_f32_e32 v140, v156, v157
	v_add_f32_e32 v147, 1.0, v147
	v_rcp_f32_e32 v157, v130
	v_pk_mul_f32 v[130:131], v[132:133], v[0:1] op_sel_hi:[1,0]
	v_pk_mul_f32 v[126:127], v[126:127], v[0:1] op_sel_hi:[1,0]
	v_pk_mul_f32 v[124:125], v[124:125], v[0:1] op_sel_hi:[1,0]
	v_pk_mul_f32 v[118:119], v[118:119], v[0:1] op_sel_hi:[1,0]
	v_rcp_f32_e32 v156, v147
	v_mul_f32_e32 v133, 0xbfb8aa3b, v131
	v_mul_f32_e32 v147, 0xbfb8aa3b, v126
	v_pk_mul_f32 v[124:125], v[130:131], v[124:125]
	v_mul_f32_e32 v131, 0xbfb8aa3b, v127
	v_pk_mul_f32 v[118:119], v[126:127], v[118:119]
	v_pk_mul_f32 v[126:127], v[128:129], v[0:1] op_sel_hi:[1,0]
	v_mul_f32_e32 v132, 0xbfb8aa3b, v130
	v_mul_f32_e32 v128, 0xbfb8aa3b, v126
	v_mul_f32_e32 v129, 0xbfb8aa3b, v127
	v_exp_f32_e32 v132, v132
	v_exp_f32_e32 v133, v133
	v_exp_f32_e32 v147, v147
	v_exp_f32_e32 v131, v131
	v_exp_f32_e32 v128, v128
	v_exp_f32_e32 v129, v129
	v_add_f32_e32 v132, 1.0, v132
	v_add_f32_e32 v133, 1.0, v133
	v_add_f32_e32 v130, 1.0, v147
	v_add_f32_e32 v131, 1.0, v131
	v_add_f32_e32 v128, 1.0, v128
	v_add_f32_e32 v129, 1.0, v129
	v_rcp_f32_e32 v132, v132
	v_rcp_f32_e32 v133, v133
	v_rcp_f32_e32 v130, v130
	v_rcp_f32_e32 v131, v131
	v_rcp_f32_e32 v128, v128
	v_rcp_f32_e32 v129, v129
	s_mul_hi_i32 s39, s21, 0x1414000
	s_mul_i32 s21, s21, 0x1414000
	v_bitop3_b32 v149, s19, v230, v97 bitop3:0xc8
	v_pk_mul_f32 v[120:121], v[120:121], v[0:1] op_sel_hi:[1,0]
	s_add_u32 s38, s4, s21
	v_pk_mul_f32 v[120:121], v[126:127], v[120:121]
	v_mul_u32_u24_e32 v0, 0xb00, v149
	v_ashrrev_i32_e32 v185, 31, v184
	v_pk_mul_f32 v[122:123], v[122:123], v[156:157]
	v_pk_mul_f32 v[124:125], v[124:125], v[132:133]
	v_pk_mul_f32 v[118:119], v[118:119], v[130:131]
	v_pk_mul_f32 v[126:127], v[120:121], v[128:129]
	s_addc_u32 s39, s5, s39
	v_lshlrev_b32_e32 v0, 1, v0
	v_cvt_pk_bf16_f32 v120, v122, v123
	v_cvt_pk_bf16_f32 v121, v124, v125
	v_cvt_pk_bf16_f32 v122, v118, v119
	v_cvt_pk_bf16_f32 v123, v126, v127
	v_lshl_add_u64 v[124:125], s[38:39], 0, v[0:1]
	v_lshlrev_b64 v[118:119], 1, v[184:185]
	v_pk_mul_f32 v[126:127], v[114:115], v[154:155] op_sel_hi:[1,0]
	v_lshl_add_u64 v[114:115], v[124:125], 0, v[118:119]
	v_mul_f32_e32 v0, 0xbfb8aa3b, v126
	v_exp_f32_e32 v0, v0
	flat_store_dwordx4 v[114:115], v[120:123]
	v_pk_mul_f32 v[116:117], v[116:117], v[154:155] op_sel_hi:[1,0]
	v_pk_mul_f32 v[106:107], v[106:107], v[154:155] op_sel_hi:[1,0]
	v_mul_f32_e32 v120, 0xbfb8aa3b, v127
	v_exp_f32_e32 v121, v120
	v_add_f32_e32 v0, 1.0, v0
	v_rcp_f32_e32 v120, v0
	v_mul_f32_e32 v122, 0xbfb8aa3b, v117
	v_add_f32_e32 v0, 1.0, v121
	v_rcp_f32_e32 v121, v0
	v_mul_f32_e32 v0, 0xbfb8aa3b, v116
	v_exp_f32_e32 v0, v0
	v_exp_f32_e32 v122, v122
	v_pk_mul_f32 v[106:107], v[126:127], v[106:107]
	v_pk_mul_f32 v[110:111], v[110:111], v[154:155] op_sel_hi:[1,0]
	v_add_f32_e32 v0, 1.0, v0
	v_pk_mul_f32 v[106:107], v[106:107], v[120:121]
	v_rcp_f32_e32 v120, v0
	v_add_f32_e32 v0, 1.0, v122
	v_rcp_f32_e32 v121, v0
	v_mul_f32_e32 v0, 0xbfb8aa3b, v110
	v_pk_mul_f32 v[108:109], v[108:109], v[154:155] op_sel_hi:[1,0]
	v_pk_mul_f32 v[102:103], v[102:103], v[154:155] op_sel_hi:[1,0]
	v_exp_f32_e32 v0, v0
	v_pk_mul_f32 v[108:109], v[116:117], v[108:109]
	v_mul_f32_e32 v116, 0xbfb8aa3b, v111
	v_pk_mul_f32 v[102:103], v[110:111], v[102:103]
	v_pk_mul_f32 v[110:111], v[112:113], v[154:155] op_sel_hi:[1,0]
	v_exp_f32_e32 v117, v116
	v_mul_f32_e32 v112, 0xbfb8aa3b, v110
	v_exp_f32_e32 v112, v112
	v_mul_f32_e32 v113, 0xbfb8aa3b, v111
	v_exp_f32_e32 v113, v113
	v_add_f32_e32 v0, 1.0, v0
	v_rcp_f32_e32 v116, v0
	v_add_f32_e32 v0, 1.0, v117
	v_rcp_f32_e32 v117, v0
	v_add_f32_e32 v0, 1.0, v112
	v_rcp_f32_e32 v112, v0
	v_add_f32_e32 v0, 1.0, v113
	v_rcp_f32_e32 v113, v0
	v_pk_mul_f32 v[116:117], v[102:103], v[116:117]
	v_pk_mul_f32 v[102:103], v[104:105], v[154:155] op_sel_hi:[1,0]
	s_mov_b32 s21, 0x16000
	v_pk_mul_f32 v[102:103], v[110:111], v[102:103]
	v_pk_mul_f32 v[108:109], v[108:109], v[120:121]
	v_pk_mul_f32 v[110:111], v[102:103], v[112:113]
	v_cvt_pk_bf16_f32 v102, v106, v107
	v_pk_mul_f32 v[98:99], v[98:99], v[152:153] op_sel_hi:[1,0]
	v_add_co_u32_e32 v106, vcc, s21, v114
	v_cvt_pk_bf16_f32 v103, v108, v109
	v_cvt_pk_bf16_f32 v104, v116, v117
	v_cvt_pk_bf16_f32 v105, v110, v111
	v_mul_f32_e32 v0, 0xbfb8aa3b, v98
	v_addc_co_u32_e32 v107, vcc, 0, v115, vcc
	v_exp_f32_e32 v0, v0
	flat_store_dwordx4 v[106:107], v[102:105]
	v_pk_mul_f32 v[86:87], v[86:87], v[152:153] op_sel_hi:[1,0]
	v_pk_mul_f32 v[90:91], v[90:91], v[152:153] op_sel_hi:[1,0]
	v_mul_f32_e32 v102, 0xbfb8aa3b, v99
	v_exp_f32_e32 v103, v102
	v_add_f32_e32 v0, 1.0, v0
	v_rcp_f32_e32 v102, v0
	v_pk_mul_f32 v[86:87], v[98:99], v[86:87]
	v_add_f32_e32 v0, 1.0, v103
	v_pk_mul_f32 v[98:99], v[100:101], v[152:153] op_sel_hi:[1,0]
	v_rcp_f32_e32 v103, v0
	v_mul_f32_e32 v0, 0xbfb8aa3b, v98
	v_exp_f32_e32 v0, v0
	v_mul_f32_e32 v100, 0xbfb8aa3b, v99
	v_exp_f32_e32 v101, v100
	v_pk_mul_f32 v[88:89], v[88:89], v[152:153] op_sel_hi:[1,0]
	v_add_f32_e32 v0, 1.0, v0
	v_rcp_f32_e32 v100, v0
	v_add_f32_e32 v0, 1.0, v101
	v_rcp_f32_e32 v101, v0
	v_mul_f32_e32 v0, 0xbfb8aa3b, v90
	v_pk_mul_f32 v[82:83], v[82:83], v[152:153] op_sel_hi:[1,0]
	v_exp_f32_e32 v0, v0
	v_pk_mul_f32 v[88:89], v[98:99], v[88:89]
	v_mul_f32_e32 v98, 0xbfb8aa3b, v91
	v_pk_mul_f32 v[82:83], v[90:91], v[82:83]
	v_pk_mul_f32 v[90:91], v[92:93], v[152:153] op_sel_hi:[1,0]
	v_exp_f32_e32 v99, v98
	v_mul_f32_e32 v92, 0xbfb8aa3b, v90
	v_exp_f32_e32 v92, v92
	v_mul_f32_e32 v93, 0xbfb8aa3b, v91
	v_exp_f32_e32 v93, v93
	v_add_f32_e32 v0, 1.0, v0
	v_rcp_f32_e32 v98, v0
	v_add_f32_e32 v0, 1.0, v99
	v_rcp_f32_e32 v99, v0
	v_add_f32_e32 v0, 1.0, v92
	v_rcp_f32_e32 v92, v0
	v_add_f32_e32 v0, 1.0, v93
	v_rcp_f32_e32 v93, v0
	v_pk_mul_f32 v[98:99], v[82:83], v[98:99]
	v_pk_mul_f32 v[82:83], v[84:85], v[152:153] op_sel_hi:[1,0]
	v_pk_mul_f32 v[86:87], v[86:87], v[102:103]
	v_pk_mul_f32 v[82:83], v[90:91], v[82:83]
	s_mov_b32 s40, 0x2c000
	v_pk_mul_f32 v[88:89], v[88:89], v[100:101]
	v_pk_mul_f32 v[90:91], v[82:83], v[92:93]
	v_cvt_pk_bf16_f32 v82, v86, v87
	v_pk_mul_f32 v[78:79], v[78:79], v[150:151] op_sel_hi:[1,0]
	v_add_co_u32_e32 v86, vcc, s40, v114
	v_cvt_pk_bf16_f32 v83, v88, v89
	v_cvt_pk_bf16_f32 v84, v98, v99
	v_cvt_pk_bf16_f32 v85, v90, v91
	v_mul_f32_e32 v0, 0xbfb8aa3b, v78
	v_addc_co_u32_e32 v87, vcc, 0, v115, vcc
	v_exp_f32_e32 v0, v0
	flat_store_dwordx4 v[86:87], v[82:85]
	v_pk_mul_f32 v[70:71], v[70:71], v[150:151] op_sel_hi:[1,0]
	v_pk_mul_f32 v[74:75], v[74:75], v[150:151] op_sel_hi:[1,0]
	v_mul_f32_e32 v82, 0xbfb8aa3b, v79
	v_exp_f32_e32 v83, v82
	v_add_f32_e32 v0, 1.0, v0
	v_rcp_f32_e32 v82, v0
	v_pk_mul_f32 v[70:71], v[78:79], v[70:71]
	v_add_f32_e32 v0, 1.0, v83
	v_pk_mul_f32 v[78:79], v[80:81], v[150:151] op_sel_hi:[1,0]
	v_rcp_f32_e32 v83, v0
	v_mul_f32_e32 v0, 0xbfb8aa3b, v78
	v_exp_f32_e32 v0, v0
	v_mul_f32_e32 v80, 0xbfb8aa3b, v79
	v_exp_f32_e32 v81, v80
	v_pk_mul_f32 v[72:73], v[72:73], v[150:151] op_sel_hi:[1,0]
	v_add_f32_e32 v0, 1.0, v0
	v_rcp_f32_e32 v80, v0
	v_add_f32_e32 v0, 1.0, v81
	v_rcp_f32_e32 v81, v0
	v_mul_f32_e32 v0, 0xbfb8aa3b, v74
	v_pk_mul_f32 v[66:67], v[66:67], v[150:151] op_sel_hi:[1,0]
	v_exp_f32_e32 v0, v0
	v_pk_mul_f32 v[72:73], v[78:79], v[72:73]
	v_mul_f32_e32 v78, 0xbfb8aa3b, v75
	v_pk_mul_f32 v[66:67], v[74:75], v[66:67]
	v_pk_mul_f32 v[74:75], v[76:77], v[150:151] op_sel_hi:[1,0]
	v_exp_f32_e32 v79, v78
	v_mul_f32_e32 v76, 0xbfb8aa3b, v74
	v_exp_f32_e32 v76, v76
	v_mul_f32_e32 v77, 0xbfb8aa3b, v75
	v_exp_f32_e32 v77, v77
	v_add_f32_e32 v0, 1.0, v0
	v_rcp_f32_e32 v78, v0
	v_add_f32_e32 v0, 1.0, v79
	v_rcp_f32_e32 v79, v0
	v_add_f32_e32 v0, 1.0, v76
	v_rcp_f32_e32 v76, v0
	v_add_f32_e32 v0, 1.0, v77
	v_rcp_f32_e32 v77, v0
	v_pk_mul_f32 v[78:79], v[66:67], v[78:79]
	v_pk_mul_f32 v[66:67], v[68:69], v[150:151] op_sel_hi:[1,0]
	v_pk_mul_f32 v[70:71], v[70:71], v[82:83]
	v_pk_mul_f32 v[66:67], v[74:75], v[66:67]
	s_mov_b32 s19, 0x42000
	v_pk_mul_f32 v[72:73], v[72:73], v[80:81]
	v_pk_mul_f32 v[74:75], v[66:67], v[76:77]
	v_cvt_pk_bf16_f32 v66, v70, v71
	v_add_co_u32_e32 v70, vcc, s19, v114
	v_pk_mul_f32 v[62:63], v[62:63], v[146:147] op_sel_hi:[1,0]
	v_cvt_pk_bf16_f32 v67, v72, v73
	v_cvt_pk_bf16_f32 v68, v78, v79
	v_cvt_pk_bf16_f32 v69, v74, v75
	v_addc_co_u32_e32 v71, vcc, 0, v115, vcc
	v_mul_f32_e32 v0, 0xbfb8aa3b, v62
	flat_store_dwordx4 v[70:71], v[66:69]
	v_exp_f32_e32 v0, v0
	v_pk_mul_f32 v[54:55], v[54:55], v[146:147] op_sel_hi:[1,0]
	v_mul_f32_e32 v66, 0xbfb8aa3b, v63
	v_exp_f32_e32 v67, v66
	v_add_f32_e32 v0, 1.0, v0
	v_rcp_f32_e32 v66, v0
	v_pk_mul_f32 v[54:55], v[62:63], v[54:55]
	v_add_f32_e32 v0, 1.0, v67
	v_pk_mul_f32 v[62:63], v[64:65], v[146:147] op_sel_hi:[1,0]
	v_rcp_f32_e32 v67, v0
	v_mul_f32_e32 v0, 0xbfb8aa3b, v62
	v_exp_f32_e32 v0, v0
	v_mul_f32_e32 v64, 0xbfb8aa3b, v63
	v_exp_f32_e32 v65, v64
	v_pk_mul_f32 v[58:59], v[58:59], v[146:147] op_sel_hi:[1,0]
	v_add_f32_e32 v0, 1.0, v0
	v_rcp_f32_e32 v64, v0
	v_add_f32_e32 v0, 1.0, v65
	v_rcp_f32_e32 v65, v0
	v_mul_f32_e32 v0, 0xbfb8aa3b, v58
	v_pk_mul_f32 v[56:57], v[56:57], v[146:147] op_sel_hi:[1,0]
	v_pk_mul_f32 v[50:51], v[50:51], v[146:147] op_sel_hi:[1,0]
	v_exp_f32_e32 v0, v0
	v_pk_mul_f32 v[56:57], v[62:63], v[56:57]
	v_mul_f32_e32 v62, 0xbfb8aa3b, v59
	v_pk_mul_f32 v[50:51], v[58:59], v[50:51]
	v_pk_mul_f32 v[58:59], v[60:61], v[146:147] op_sel_hi:[1,0]
	v_exp_f32_e32 v63, v62
	v_mul_f32_e32 v60, 0xbfb8aa3b, v58
	v_exp_f32_e32 v60, v60
	v_mul_f32_e32 v61, 0xbfb8aa3b, v59
	v_exp_f32_e32 v61, v61
	v_add_f32_e32 v0, 1.0, v0
	v_rcp_f32_e32 v62, v0
	v_add_f32_e32 v0, 1.0, v63
	v_rcp_f32_e32 v63, v0
	v_add_f32_e32 v0, 1.0, v60
	v_rcp_f32_e32 v60, v0
	v_add_f32_e32 v0, 1.0, v61
	v_rcp_f32_e32 v61, v0
	v_pk_mul_f32 v[62:63], v[50:51], v[62:63]
	v_pk_mul_f32 v[50:51], v[52:53], v[146:147] op_sel_hi:[1,0]
	v_and_b32_e32 v69, 0x7cf, v148
	v_pk_mul_f32 v[54:55], v[54:55], v[66:67]
	v_pk_mul_f32 v[50:51], v[58:59], v[50:51]
	v_ashrrev_i32_e32 v68, 11, v148
	v_pk_mul_f32 v[58:59], v[50:51], v[60:61]
	v_cvt_pk_bf16_f32 v50, v54, v55
	v_mov_b64_e32 v[54:55], s[4:5]
	s_mov_b32 s19, 0x1414000
	v_mul_u32_u24_e32 v0, 0xb00, v69
	v_pk_mul_f32 v[56:57], v[56:57], v[64:65]
	v_mad_i64_i32 v[54:55], s[38:39], v68, s19, v[54:55]
	v_lshlrev_b32_e32 v0, 1, v0
	v_cvt_pk_bf16_f32 v51, v56, v57
	v_lshl_add_u64 v[54:55], v[54:55], 0, v[0:1]
	v_pk_mul_f32 v[56:57], v[46:47], v[144:145] op_sel_hi:[1,0]
	v_cvt_pk_bf16_f32 v52, v62, v63
	v_cvt_pk_bf16_f32 v53, v58, v59
	v_mul_f32_e32 v0, 0xbfb8aa3b, v56
	v_lshl_add_u64 v[46:47], v[54:55], 0, v[118:119]
	v_exp_f32_e32 v0, v0
	flat_store_dwordx4 v[46:47], v[50:53]
	v_pk_mul_f32 v[48:49], v[48:49], v[144:145] op_sel_hi:[1,0]
	v_pk_mul_f32 v[38:39], v[38:39], v[144:145] op_sel_hi:[1,0]
	v_mul_f32_e32 v50, 0xbfb8aa3b, v57
	v_exp_f32_e32 v51, v50
	v_add_f32_e32 v0, 1.0, v0
	v_rcp_f32_e32 v50, v0
	v_mul_f32_e32 v52, 0xbfb8aa3b, v49
	v_add_f32_e32 v0, 1.0, v51
	v_rcp_f32_e32 v51, v0
	v_mul_f32_e32 v0, 0xbfb8aa3b, v48
	v_exp_f32_e32 v0, v0
	v_exp_f32_e32 v52, v52
	v_pk_mul_f32 v[38:39], v[56:57], v[38:39]
	v_pk_mul_f32 v[42:43], v[42:43], v[144:145] op_sel_hi:[1,0]
	v_add_f32_e32 v0, 1.0, v0
	v_pk_mul_f32 v[38:39], v[38:39], v[50:51]
	v_rcp_f32_e32 v50, v0
	v_add_f32_e32 v0, 1.0, v52
	v_rcp_f32_e32 v51, v0
	v_mul_f32_e32 v0, 0xbfb8aa3b, v42
	v_pk_mul_f32 v[40:41], v[40:41], v[144:145] op_sel_hi:[1,0]
	v_pk_mul_f32 v[34:35], v[34:35], v[144:145] op_sel_hi:[1,0]
	v_exp_f32_e32 v0, v0
	v_pk_mul_f32 v[40:41], v[48:49], v[40:41]
	v_mul_f32_e32 v48, 0xbfb8aa3b, v43
	v_pk_mul_f32 v[34:35], v[42:43], v[34:35]
	v_pk_mul_f32 v[42:43], v[44:45], v[144:145] op_sel_hi:[1,0]
	v_exp_f32_e32 v49, v48
	v_mul_f32_e32 v44, 0xbfb8aa3b, v42
	v_exp_f32_e32 v44, v44
	v_mul_f32_e32 v45, 0xbfb8aa3b, v43
	v_exp_f32_e32 v45, v45
	v_add_f32_e32 v0, 1.0, v0
	v_rcp_f32_e32 v48, v0
	v_add_f32_e32 v0, 1.0, v49
	v_rcp_f32_e32 v49, v0
	v_add_f32_e32 v0, 1.0, v44
	v_rcp_f32_e32 v44, v0
	v_add_f32_e32 v0, 1.0, v45
	v_rcp_f32_e32 v45, v0
	v_pk_mul_f32 v[48:49], v[34:35], v[48:49]
	v_pk_mul_f32 v[34:35], v[36:37], v[144:145] op_sel_hi:[1,0]
	v_pk_mul_f32 v[40:41], v[40:41], v[50:51]
	v_pk_mul_f32 v[34:35], v[42:43], v[34:35]
	v_pk_mul_f32 v[30:31], v[30:31], v[142:143] op_sel_hi:[1,0]
	v_pk_mul_f32 v[42:43], v[34:35], v[44:45]
	v_cvt_pk_bf16_f32 v34, v38, v39
	v_add_co_u32_e32 v38, vcc, s21, v46
	v_cvt_pk_bf16_f32 v35, v40, v41
	v_cvt_pk_bf16_f32 v36, v48, v49
	v_cvt_pk_bf16_f32 v37, v42, v43
	v_mul_f32_e32 v0, 0xbfb8aa3b, v30
	v_addc_co_u32_e32 v39, vcc, 0, v47, vcc
	v_exp_f32_e32 v0, v0
	flat_store_dwordx4 v[38:39], v[34:37]
	v_pk_mul_f32 v[22:23], v[22:23], v[142:143] op_sel_hi:[1,0]
	v_pk_mul_f32 v[26:27], v[26:27], v[142:143] op_sel_hi:[1,0]
	v_mul_f32_e32 v34, 0xbfb8aa3b, v31
	v_exp_f32_e32 v35, v34
	v_add_f32_e32 v0, 1.0, v0
	v_rcp_f32_e32 v34, v0
	v_pk_mul_f32 v[22:23], v[30:31], v[22:23]
	v_add_f32_e32 v0, 1.0, v35
	v_pk_mul_f32 v[30:31], v[32:33], v[142:143] op_sel_hi:[1,0]
	v_rcp_f32_e32 v35, v0
	v_mul_f32_e32 v0, 0xbfb8aa3b, v30
	v_exp_f32_e32 v0, v0
	v_mul_f32_e32 v32, 0xbfb8aa3b, v31
	v_exp_f32_e32 v33, v32
	v_pk_mul_f32 v[24:25], v[24:25], v[142:143] op_sel_hi:[1,0]
	v_add_f32_e32 v0, 1.0, v0
	v_rcp_f32_e32 v32, v0
	v_add_f32_e32 v0, 1.0, v33
	v_rcp_f32_e32 v33, v0
	v_mul_f32_e32 v0, 0xbfb8aa3b, v26
	v_pk_mul_f32 v[18:19], v[18:19], v[142:143] op_sel_hi:[1,0]
	v_exp_f32_e32 v0, v0
	v_pk_mul_f32 v[24:25], v[30:31], v[24:25]
	v_mul_f32_e32 v30, 0xbfb8aa3b, v27
	v_pk_mul_f32 v[18:19], v[26:27], v[18:19]
	v_pk_mul_f32 v[26:27], v[28:29], v[142:143] op_sel_hi:[1,0]
	v_exp_f32_e32 v31, v30
	v_mul_f32_e32 v28, 0xbfb8aa3b, v26
	v_exp_f32_e32 v28, v28
	v_mul_f32_e32 v29, 0xbfb8aa3b, v27
	v_exp_f32_e32 v29, v29
	v_add_f32_e32 v0, 1.0, v0
	v_rcp_f32_e32 v30, v0
	v_add_f32_e32 v0, 1.0, v31
	v_rcp_f32_e32 v31, v0
	v_add_f32_e32 v0, 1.0, v28
	v_fmamk_f32 v140, v140, 0x3a800000, v222
	v_rcp_f32_e32 v28, v0
	v_add_f32_e32 v0, 1.0, v29
	v_rsq_f32_e32 v140, v140
	v_rcp_f32_e32 v29, v0
	v_pk_mul_f32 v[30:31], v[18:19], v[30:31]
	v_pk_mul_f32 v[18:19], v[20:21], v[142:143] op_sel_hi:[1,0]
	v_pk_mul_f32 v[22:23], v[22:23], v[34:35]
	v_pk_mul_f32 v[18:19], v[26:27], v[18:19]
	v_pk_mul_f32 v[24:25], v[24:25], v[32:33]
	v_pk_mul_f32 v[26:27], v[18:19], v[28:29]
	v_cvt_pk_bf16_f32 v18, v22, v23
	v_pk_mul_f32 v[14:15], v[14:15], v[140:141] op_sel_hi:[1,0]
	v_add_co_u32_e32 v22, vcc, s40, v46
	v_cvt_pk_bf16_f32 v19, v24, v25
	v_cvt_pk_bf16_f32 v20, v30, v31
	v_cvt_pk_bf16_f32 v21, v26, v27
	v_mul_f32_e32 v0, 0xbfb8aa3b, v14
	v_addc_co_u32_e32 v23, vcc, 0, v47, vcc
	v_exp_f32_e32 v0, v0
	flat_store_dwordx4 v[22:23], v[18:21]
	v_pk_mul_f32 v[6:7], v[6:7], v[140:141] op_sel_hi:[1,0]
	v_pk_mul_f32 v[10:11], v[10:11], v[140:141] op_sel_hi:[1,0]
	v_mul_f32_e32 v18, 0xbfb8aa3b, v15
	v_exp_f32_e32 v19, v18
	v_add_f32_e32 v0, 1.0, v0
	v_rcp_f32_e32 v18, v0
	v_pk_mul_f32 v[6:7], v[14:15], v[6:7]
	v_add_f32_e32 v0, 1.0, v19
	v_pk_mul_f32 v[14:15], v[16:17], v[140:141] op_sel_hi:[1,0]
	v_rcp_f32_e32 v19, v0
	v_mul_f32_e32 v0, 0xbfb8aa3b, v14
	v_exp_f32_e32 v0, v0
	v_mul_f32_e32 v16, 0xbfb8aa3b, v15
	v_exp_f32_e32 v17, v16
	v_pk_mul_f32 v[8:9], v[8:9], v[140:141] op_sel_hi:[1,0]
	v_add_f32_e32 v0, 1.0, v0
	v_rcp_f32_e32 v16, v0
	v_add_f32_e32 v0, 1.0, v17
	v_rcp_f32_e32 v17, v0
	v_mul_f32_e32 v0, 0xbfb8aa3b, v10
	v_pk_mul_f32 v[2:3], v[2:3], v[140:141] op_sel_hi:[1,0]
	v_exp_f32_e32 v0, v0
	v_pk_mul_f32 v[8:9], v[14:15], v[8:9]
	v_mul_f32_e32 v14, 0xbfb8aa3b, v11
	v_pk_mul_f32 v[2:3], v[10:11], v[2:3]
	v_pk_mul_f32 v[10:11], v[12:13], v[140:141] op_sel_hi:[1,0]
	v_exp_f32_e32 v15, v14
	v_mul_f32_e32 v12, 0xbfb8aa3b, v10
	v_exp_f32_e32 v12, v12
	v_mul_f32_e32 v13, 0xbfb8aa3b, v11
	v_exp_f32_e32 v13, v13
	v_add_f32_e32 v0, 1.0, v0
	v_rcp_f32_e32 v14, v0
	v_add_f32_e32 v0, 1.0, v15
	v_rcp_f32_e32 v15, v0
	v_add_f32_e32 v0, 1.0, v12
	v_rcp_f32_e32 v12, v0
	v_add_f32_e32 v0, 1.0, v13
	v_rcp_f32_e32 v13, v0
	v_pk_mul_f32 v[14:15], v[2:3], v[14:15]
	v_pk_mul_f32 v[2:3], v[4:5], v[140:141] op_sel_hi:[1,0]
	v_pk_mul_f32 v[6:7], v[6:7], v[18:19]
	v_pk_mul_f32 v[2:3], v[10:11], v[2:3]
	v_pk_mul_f32 v[8:9], v[8:9], v[16:17]
	v_pk_mul_f32 v[10:11], v[2:3], v[12:13]
	v_cvt_pk_bf16_f32 v2, v6, v7
	v_add_co_u32_e32 v6, vcc, 0x42000, v46
	v_cvt_pk_bf16_f32 v3, v8, v9
	v_cvt_pk_bf16_f32 v4, v14, v15
	v_cvt_pk_bf16_f32 v5, v10, v11
	v_addc_co_u32_e32 v7, vcc, 0, v47, vcc
	flat_store_dwordx4 v[6:7], v[2:5]
	s_andn2_b64 vcc, exec, s[36:37]
	s_mov_b64 s[36:37], -1
	s_cbranch_vccnz .LBB0_561
	s_andn2_b64 vcc, exec, s[0:1]
	s_cbranch_vccnz .LBB0_560
	s_barrier
	s_branch .LBB0_560
